# final candidate: v17 plus 37 more clamped-exp2 denormal-rescue removals in the HGRN prep phase (bit-identical math)
# speedup vs baseline: 1.0300x; 1.0005x over previous
.LBB0_175:
	s_and_b32 s24, s39, 0xffffffe0
	v_or_b32_e32 v2, s24, v8
	v_mov_b64_e32 v[4:5], s[20:21]
	s_ashr_i32 s26, s40, 1
	v_mad_i64_i32 v[4:5], s[24:25], v2, s41, v[4:5]
	s_lshl_b32 s24, s26, 7
	s_and_b32 s33, s24, 0x380
	v_and_or_b32 v21, s38, 64, v1
	s_lshl_b32 s50, s33, 1
	v_lshl_add_u64 v[4:5], v[4:5], 0, s[50:51]
	v_lshlrev_b32_e32 v2, 1, v21
	v_lshl_add_u64 v[68:69], v[4:5], 0, v[2:3]
	s_movk_i32 s28, 0x2000
	v_add_co_u32_e32 v4, vcc, s28, v68
	s_mov_b32 s28, 0xa000
	s_nop 0
	v_addc_co_u32_e32 v5, vcc, 0, v69, vcc
	v_add_co_u32_e32 v66, vcc, s28, v68
	s_mov_b32 s28, 0x12000
	s_nop 0
	v_addc_co_u32_e32 v67, vcc, 0, v69, vcc
	v_add_co_u32_e32 v64, vcc, s28, v68
	s_mov_b32 s28, 0x1a000
	s_nop 0
	v_addc_co_u32_e32 v65, vcc, 0, v69, vcc
	v_add_co_u32_e32 v62, vcc, s28, v68
	s_mov_b32 s28, 0x23000
	s_nop 0
	v_addc_co_u32_e32 v63, vcc, 0, v69, vcc
	v_add_co_u32_e32 v32, vcc, s28, v68
	s_mov_b32 s28, 0x2b000
	s_nop 0
	v_addc_co_u32_e32 v33, vcc, 0, v69, vcc
	v_add_co_u32_e32 v34, vcc, s28, v68
	s_mov_b32 s28, 0x33000
	s_nop 0
	v_addc_co_u32_e32 v35, vcc, 0, v69, vcc
	v_add_co_u32_e32 v36, vcc, s28, v68
	global_load_dwordx2 v[6:7], v[4:5], off offset:2048
	s_nop 0
	v_addc_co_u32_e32 v37, vcc, 0, v69, vcc
	global_load_dwordx2 v[28:29], v[64:65], off offset:3072
	global_load_dwordx2 v[30:31], v[62:63], off offset:3584
	s_mov_b32 s28, 0x3b000
	global_load_dwordx2 v[32:33], v[32:33], off
	v_add_co_u32_e32 v38, vcc, s28, v68
	global_load_dwordx2 v[34:35], v[34:35], off offset:512
	s_nop 0
	v_addc_co_u32_e32 v39, vcc, 0, v69, vcc
	global_load_dwordx2 v[36:37], v[36:37], off offset:1024
	s_ashr_i32 s27, s26, 31
	global_load_dwordx2 v[4:5], v[66:67], off offset:2560
	s_lshl_b64 s[24:25], s[26:27], 11
	global_load_dwordx2 v[38:39], v[38:39], off offset:1536
	s_lshl_b64 s[26:27], s[26:27], 13
	s_mov_b32 s42, 0xffff0000
	s_add_u32 s28, s34, s26
	s_addc_u32 s29, s35, s27
	v_lshlrev_b32_e32 v72, 6, v21
	v_mov_b32_e32 v73, v3
	v_lshl_add_u64 v[48:49], s[28:29], 0, v[72:73]
	v_lshlrev_b32_e32 v50, 1, v8
	v_mov_b32_e32 v51, v3
	v_lshl_add_u64 v[48:49], v[48:49], 0, v[50:51]
	s_movk_i32 s28, 0x1000
	v_add_co_u32_e32 v82, vcc, s28, v68
	s_add_u32 s24, s36, s24
	s_nop 0
	v_addc_co_u32_e32 v83, vcc, 0, v69, vcc
	s_addc_u32 s25, s37, s25
	v_lshl_add_u64 v[60:61], v[10:11], 0, s[26:27]
	v_lshlrev_b32_e32 v19, 5, v21
	s_waitcnt vmcnt(7)
	v_and_b32_e32 v23, 0xffff, v6
	v_lshrrev_b32_e32 v6, 16, v6
	s_waitcnt vmcnt(1)
	v_lshl_or_b32 v40, v4, 16, v23
	v_and_b32_e32 v23, 0xffff, v28
	v_and_or_b32 v44, v4, s42, v6
	v_lshrrev_b32_e32 v4, 16, v28
	v_lshl_or_b32 v41, v30, 16, v23
	v_and_b32_e32 v23, 0xffff, v32
	v_and_or_b32 v45, v30, s42, v4
	v_lshrrev_b32_e32 v4, 16, v32
	v_lshl_or_b32 v42, v34, 16, v23
	v_and_b32_e32 v23, 0xffff, v36
	v_and_or_b32 v46, v34, s42, v4
	v_lshrrev_b32_e32 v4, 16, v36
	s_waitcnt vmcnt(0)
	v_lshl_or_b32 v43, v38, 16, v23
	v_and_or_b32 v47, v38, s42, v4
	v_and_b32_e32 v4, 0xffff, v7
	global_store_dwordx4 v[48:49], v[40:43], off
	global_store_dwordx4 v[48:49], v[44:47], off offset:64
	v_lshrrev_b32_e32 v6, 16, v33
	v_lshl_or_b32 v40, v5, 16, v4
	v_and_b32_e32 v4, 0xffff, v29
	v_lshl_or_b32 v41, v31, 16, v4
	v_and_b32_e32 v4, 0xffff, v33
	v_lshl_or_b32 v42, v35, 16, v4
	v_and_b32_e32 v4, 0xffff, v37
	v_lshl_or_b32 v43, v39, 16, v4
	v_lshrrev_b32_e32 v4, 16, v7
	v_and_or_b32 v4, v5, s42, v4
	v_lshrrev_b32_e32 v5, 16, v29
	v_lshrrev_b32_e32 v7, 16, v37
	v_and_or_b32 v5, v31, s42, v5
	v_and_or_b32 v6, v35, s42, v6
	v_and_or_b32 v7, v39, s42, v7
	global_store_dwordx4 v[48:49], v[40:43], off offset:128
	global_store_dwordx4 v[48:49], v[4:7], off offset:192
	global_load_dwordx2 v[4:5], v[82:83], off
	s_waitcnt vmcnt(0)
	v_lshlrev_b32_e32 v6, 16, v4
	v_and_b32_e32 v7, 0xffff0000, v4
	v_mul_f32_e32 v4, 0xbfb8aa3b, v6
	v_exp_f32_e32 v28, v4
	v_mul_f32_e32 v4, 0xbfb8aa3b, v7
	v_exp_f32_e32 v29, v4
	s_nop 0
	v_pk_add_f32 v[28:29], v[28:29], 1.0 op_sel_hi:[1,0]
	s_nop 0
	v_rcp_f32_e32 v23, v29
	s_nop 0
	v_fma_f32 v25, -v29, v23, 1.0
	v_fmac_f32_e32 v23, v25, v23
	v_div_fixup_f32 v29, v23, v29, 1.0
	v_rcp_f32_e32 v23, v28
	s_nop 0
	v_fma_f32 v25, -v28, v23, 1.0
	v_fmac_f32_e32 v23, v25, v23
	v_div_fixup_f32 v28, v23, v28, 1.0
	v_lshlrev_b32_e32 v4, 16, v5
	v_and_b32_e32 v5, 0xffff0000, v5
	v_pk_mul_f32 v[46:47], v[28:29], v[6:7]
	v_mul_f32_e32 v6, 0xbfb8aa3b, v4
	v_mul_f32_e32 v7, 0xbfb8aa3b, v5
	v_exp_f32_e32 v6, v6
	v_exp_f32_e32 v7, v7
	s_nop 0
	v_pk_add_f32 v[6:7], v[6:7], 1.0 op_sel_hi:[1,0]
	s_nop 0
	v_rcp_f32_e32 v25, v7
	s_nop 0
	v_fma_f32 v27, -v7, v25, 1.0
	v_fmac_f32_e32 v25, v27, v25
	v_div_fixup_f32 v7, v25, v7, 1.0
	v_rcp_f32_e32 v25, v6
	s_mov_b32 s28, 0x9000
	v_fma_f32 v27, -v6, v25, 1.0
	v_fmac_f32_e32 v25, v27, v25
	v_add_co_u32_e32 v78, vcc, s28, v68
	v_div_fixup_f32 v6, v25, v6, 1.0
	s_nop 0
	v_addc_co_u32_e32 v79, vcc, 0, v69, vcc
	v_pk_mul_f32 v[30:31], v[6:7], v[4:5]
	global_load_dwordx2 v[4:5], v[78:79], off offset:512
	s_waitcnt vmcnt(0)
	v_lshlrev_b32_e32 v6, 16, v4
	v_and_b32_e32 v7, 0xffff0000, v4
	v_mul_f32_e32 v4, 0xbfb8aa3b, v6
	v_exp_f32_e32 v28, v4
	v_mul_f32_e32 v4, 0xbfb8aa3b, v7
	v_exp_f32_e32 v29, v4
	s_nop 0
	v_pk_add_f32 v[28:29], v[28:29], 1.0 op_sel_hi:[1,0]
	s_nop 0
	v_rcp_f32_e32 v23, v29
	s_nop 0
	v_fma_f32 v25, -v29, v23, 1.0
	v_fmac_f32_e32 v23, v25, v23
	v_div_fixup_f32 v29, v23, v29, 1.0
	v_rcp_f32_e32 v23, v28
	s_nop 0
	v_fma_f32 v25, -v28, v23, 1.0
	v_fmac_f32_e32 v23, v25, v23
	v_div_fixup_f32 v28, v23, v28, 1.0
	v_lshlrev_b32_e32 v4, 16, v5
	v_and_b32_e32 v5, 0xffff0000, v5
	v_pk_mul_f32 v[44:45], v[28:29], v[6:7]
	v_mul_f32_e32 v6, 0xbfb8aa3b, v4
	v_mul_f32_e32 v7, 0xbfb8aa3b, v5
	v_exp_f32_e32 v6, v6
	v_exp_f32_e32 v7, v7
	s_nop 0
	v_pk_add_f32 v[6:7], v[6:7], 1.0 op_sel_hi:[1,0]
	s_nop 0
	v_rcp_f32_e32 v25, v7
	s_nop 0
	v_fma_f32 v27, -v7, v25, 1.0
	v_fmac_f32_e32 v25, v27, v25
	v_div_fixup_f32 v7, v25, v7, 1.0
	v_rcp_f32_e32 v25, v6
	s_mov_b32 s28, 0x11000
	v_fma_f32 v27, -v6, v25, 1.0
	v_fmac_f32_e32 v25, v27, v25
	v_add_co_u32_e32 v80, vcc, s28, v68
	v_div_fixup_f32 v6, v25, v6, 1.0
	s_nop 0
	v_addc_co_u32_e32 v81, vcc, 0, v69, vcc
	v_pk_mul_f32 v[28:29], v[6:7], v[4:5]
	global_load_dwordx2 v[4:5], v[80:81], off offset:1024
	s_waitcnt vmcnt(0)
	v_lshlrev_b32_e32 v6, 16, v4
	v_and_b32_e32 v7, 0xffff0000, v4
	v_mul_f32_e32 v4, 0xbfb8aa3b, v6
	v_exp_f32_e32 v32, v4
	v_mul_f32_e32 v4, 0xbfb8aa3b, v7
	v_exp_f32_e32 v33, v4
	s_nop 0
	v_pk_add_f32 v[32:33], v[32:33], 1.0 op_sel_hi:[1,0]
	s_nop 0
	v_rcp_f32_e32 v23, v33
	s_nop 0
	v_fma_f32 v25, -v33, v23, 1.0
	v_fmac_f32_e32 v23, v25, v23
	v_div_fixup_f32 v33, v23, v33, 1.0
	v_rcp_f32_e32 v23, v32
	s_nop 0
	v_fma_f32 v25, -v32, v23, 1.0
	v_fmac_f32_e32 v23, v25, v23
	v_div_fixup_f32 v32, v23, v32, 1.0
	v_lshlrev_b32_e32 v4, 16, v5
	v_and_b32_e32 v5, 0xffff0000, v5
	v_pk_mul_f32 v[58:59], v[32:33], v[6:7]
	v_mul_f32_e32 v6, 0xbfb8aa3b, v4
	v_mul_f32_e32 v7, 0xbfb8aa3b, v5
	v_exp_f32_e32 v6, v6
	v_exp_f32_e32 v7, v7
	s_nop 0
	v_pk_add_f32 v[6:7], v[6:7], 1.0 op_sel_hi:[1,0]
	s_nop 0
	v_rcp_f32_e32 v25, v7
	s_nop 0
	v_fma_f32 v27, -v7, v25, 1.0
	v_fmac_f32_e32 v25, v27, v25
	v_div_fixup_f32 v7, v25, v7, 1.0
	v_rcp_f32_e32 v25, v6
	s_mov_b32 s28, 0x19000
	v_fma_f32 v27, -v6, v25, 1.0
	v_fmac_f32_e32 v25, v27, v25
	v_add_co_u32_e32 v76, vcc, s28, v68
	v_div_fixup_f32 v6, v25, v6, 1.0
	s_nop 0
	v_addc_co_u32_e32 v77, vcc, 0, v69, vcc
	v_pk_mul_f32 v[42:43], v[6:7], v[4:5]
	global_load_dwordx2 v[4:5], v[76:77], off offset:1536
	s_waitcnt vmcnt(0)
	v_lshlrev_b32_e32 v6, 16, v4
	v_and_b32_e32 v7, 0xffff0000, v4
	v_mul_f32_e32 v4, 0xbfb8aa3b, v6
	v_exp_f32_e32 v32, v4
	v_mul_f32_e32 v4, 0xbfb8aa3b, v7
	v_exp_f32_e32 v33, v4
	s_nop 0
	v_pk_add_f32 v[32:33], v[32:33], 1.0 op_sel_hi:[1,0]
	s_nop 0
	v_rcp_f32_e32 v23, v33
	s_nop 0
	v_fma_f32 v25, -v33, v23, 1.0
	v_fmac_f32_e32 v23, v25, v23
	v_div_fixup_f32 v33, v23, v33, 1.0
	v_rcp_f32_e32 v23, v32
	s_nop 0
	v_fma_f32 v25, -v32, v23, 1.0
	v_fmac_f32_e32 v23, v25, v23
	v_div_fixup_f32 v32, v23, v32, 1.0
	v_lshlrev_b32_e32 v4, 16, v5
	v_and_b32_e32 v5, 0xffff0000, v5
	v_pk_mul_f32 v[56:57], v[32:33], v[6:7]
	v_mul_f32_e32 v6, 0xbfb8aa3b, v4
	v_mul_f32_e32 v7, 0xbfb8aa3b, v5
	v_exp_f32_e32 v6, v6
	v_exp_f32_e32 v7, v7
	s_nop 0
	v_pk_add_f32 v[6:7], v[6:7], 1.0 op_sel_hi:[1,0]
	s_nop 0
	v_rcp_f32_e32 v25, v7
	s_nop 0
	v_fma_f32 v27, -v7, v25, 1.0
	v_fmac_f32_e32 v25, v27, v25
	v_div_fixup_f32 v7, v25, v7, 1.0
	v_rcp_f32_e32 v25, v6
	s_mov_b32 s28, 0x21000
	v_fma_f32 v27, -v6, v25, 1.0
	v_fmac_f32_e32 v25, v27, v25
	v_div_fixup_f32 v6, v25, v6, 1.0
	v_pk_mul_f32 v[40:41], v[6:7], v[4:5]
	v_add_co_u32_e32 v4, vcc, s28, v68
	s_nop 1
	v_addc_co_u32_e32 v5, vcc, 0, v69, vcc
	global_load_dwordx2 v[4:5], v[4:5], off offset:2048
	s_waitcnt vmcnt(0)
	v_lshlrev_b32_e32 v6, 16, v4
	v_and_b32_e32 v7, 0xffff0000, v4
	v_mul_f32_e32 v4, 0xbfb8aa3b, v6
	v_exp_f32_e32 v32, v4
	v_mul_f32_e32 v4, 0xbfb8aa3b, v7
	v_exp_f32_e32 v33, v4
	s_nop 0
	v_pk_add_f32 v[32:33], v[32:33], 1.0 op_sel_hi:[1,0]
	s_nop 0
	v_rcp_f32_e32 v23, v33
	s_nop 0
	v_fma_f32 v25, -v33, v23, 1.0
	v_fmac_f32_e32 v23, v25, v23
	v_div_fixup_f32 v33, v23, v33, 1.0
	v_rcp_f32_e32 v23, v32
	s_nop 0
	v_fma_f32 v25, -v32, v23, 1.0
	v_fmac_f32_e32 v23, v25, v23
	v_div_fixup_f32 v32, v23, v32, 1.0
	v_lshlrev_b32_e32 v4, 16, v5
	v_and_b32_e32 v5, 0xffff0000, v5
	v_pk_mul_f32 v[54:55], v[32:33], v[6:7]
	v_mul_f32_e32 v6, 0xbfb8aa3b, v4
	v_mul_f32_e32 v7, 0xbfb8aa3b, v5
	v_exp_f32_e32 v6, v6
	v_exp_f32_e32 v7, v7
	s_nop 0
	v_pk_add_f32 v[6:7], v[6:7], 1.0 op_sel_hi:[1,0]
	s_nop 0
	v_rcp_f32_e32 v25, v7
	s_nop 0
	v_fma_f32 v27, -v7, v25, 1.0
	v_fmac_f32_e32 v25, v27, v25
	v_div_fixup_f32 v7, v25, v7, 1.0
	v_rcp_f32_e32 v25, v6
	s_mov_b32 s28, 0x29000
	v_fma_f32 v27, -v6, v25, 1.0
	v_fmac_f32_e32 v25, v27, v25
	v_div_fixup_f32 v6, v25, v6, 1.0
	v_pk_mul_f32 v[38:39], v[6:7], v[4:5]
	v_add_co_u32_e32 v4, vcc, s28, v68
	s_nop 1
	v_addc_co_u32_e32 v5, vcc, 0, v69, vcc
	global_load_dwordx2 v[4:5], v[4:5], off offset:2560
	s_waitcnt vmcnt(0)
	v_lshlrev_b32_e32 v6, 16, v4
	v_and_b32_e32 v7, 0xffff0000, v4
	v_mul_f32_e32 v4, 0xbfb8aa3b, v6
	v_exp_f32_e32 v32, v4
	v_mul_f32_e32 v4, 0xbfb8aa3b, v7
	v_exp_f32_e32 v33, v4
	s_nop 0
	v_pk_add_f32 v[32:33], v[32:33], 1.0 op_sel_hi:[1,0]
	s_nop 0
	v_rcp_f32_e32 v23, v33
	s_nop 0
	v_fma_f32 v25, -v33, v23, 1.0
	v_fmac_f32_e32 v23, v25, v23
	v_div_fixup_f32 v33, v23, v33, 1.0
	v_rcp_f32_e32 v23, v32
	s_nop 0
	v_fma_f32 v25, -v32, v23, 1.0
	v_fmac_f32_e32 v23, v25, v23
	v_div_fixup_f32 v32, v23, v32, 1.0
	v_lshlrev_b32_e32 v4, 16, v5
	v_and_b32_e32 v5, 0xffff0000, v5
	v_pk_mul_f32 v[52:53], v[32:33], v[6:7]
	v_mul_f32_e32 v6, 0xbfb8aa3b, v4
	v_mul_f32_e32 v7, 0xbfb8aa3b, v5
	v_exp_f32_e32 v6, v6
	v_exp_f32_e32 v7, v7
	s_nop 0
	v_pk_add_f32 v[6:7], v[6:7], 1.0 op_sel_hi:[1,0]
	s_nop 0
	v_rcp_f32_e32 v25, v7
	s_nop 0
	v_fma_f32 v27, -v7, v25, 1.0
	v_fmac_f32_e32 v25, v27, v25
	v_div_fixup_f32 v7, v25, v7, 1.0
	v_rcp_f32_e32 v25, v6
	s_mov_b32 s28, 0x31000
	v_fma_f32 v27, -v6, v25, 1.0
	v_fmac_f32_e32 v25, v27, v25
	v_div_fixup_f32 v6, v25, v6, 1.0
	v_pk_mul_f32 v[36:37], v[6:7], v[4:5]
	v_add_co_u32_e32 v4, vcc, s28, v68
	s_nop 1
	v_addc_co_u32_e32 v5, vcc, 0, v69, vcc
	global_load_dwordx2 v[4:5], v[4:5], off offset:3072
	s_waitcnt vmcnt(0)
	v_lshlrev_b32_e32 v6, 16, v4
	v_and_b32_e32 v7, 0xffff0000, v4
	v_mul_f32_e32 v4, 0xbfb8aa3b, v6
	v_exp_f32_e32 v32, v4
	v_mul_f32_e32 v4, 0xbfb8aa3b, v7
	v_exp_f32_e32 v33, v4
	s_nop 0
	v_pk_add_f32 v[32:33], v[32:33], 1.0 op_sel_hi:[1,0]
	s_nop 0
	v_rcp_f32_e32 v23, v33
	s_nop 0
	v_fma_f32 v25, -v33, v23, 1.0
	v_fmac_f32_e32 v23, v25, v23
	v_div_fixup_f32 v33, v23, v33, 1.0
	v_rcp_f32_e32 v23, v32
	s_nop 0
	v_fma_f32 v25, -v32, v23, 1.0
	v_fmac_f32_e32 v23, v25, v23
	v_div_fixup_f32 v32, v23, v32, 1.0
	v_lshlrev_b32_e32 v4, 16, v5
	v_and_b32_e32 v5, 0xffff0000, v5
	v_pk_mul_f32 v[50:51], v[32:33], v[6:7]
	v_mul_f32_e32 v6, 0xbfb8aa3b, v4
	v_mul_f32_e32 v7, 0xbfb8aa3b, v5
	v_exp_f32_e32 v6, v6
	v_exp_f32_e32 v7, v7
	s_nop 0
	v_pk_add_f32 v[6:7], v[6:7], 1.0 op_sel_hi:[1,0]
	s_nop 0
	v_rcp_f32_e32 v25, v7
	s_nop 0
	v_fma_f32 v27, -v7, v25, 1.0
	v_fmac_f32_e32 v25, v27, v25
	v_div_fixup_f32 v7, v25, v7, 1.0
	v_rcp_f32_e32 v25, v6
	s_mov_b32 s28, 0x39000
	v_fma_f32 v27, -v6, v25, 1.0
	v_fmac_f32_e32 v25, v27, v25
	v_div_fixup_f32 v6, v25, v6, 1.0
	v_pk_mul_f32 v[34:35], v[6:7], v[4:5]
	v_add_co_u32_e32 v4, vcc, s28, v68
	s_nop 1
	v_addc_co_u32_e32 v5, vcc, 0, v69, vcc
	global_load_dwordx2 v[4:5], v[4:5], off offset:3584
	s_waitcnt vmcnt(0)
	v_lshlrev_b32_e32 v6, 16, v4
	v_and_b32_e32 v7, 0xffff0000, v4
	v_mul_f32_e32 v4, 0xbfb8aa3b, v6
	v_exp_f32_e32 v32, v4
	v_mul_f32_e32 v4, 0xbfb8aa3b, v7
	v_exp_f32_e32 v33, v4
	s_nop 0
	v_pk_add_f32 v[32:33], v[32:33], 1.0 op_sel_hi:[1,0]
	s_nop 0
	v_rcp_f32_e32 v23, v33
	s_nop 0
	v_fma_f32 v25, -v33, v23, 1.0
	v_fmac_f32_e32 v23, v25, v23
	v_div_fixup_f32 v33, v23, v33, 1.0
	v_rcp_f32_e32 v23, v32
	s_nop 0
	v_fma_f32 v25, -v32, v23, 1.0
	v_fmac_f32_e32 v23, v25, v23
	v_div_fixup_f32 v32, v23, v32, 1.0
	v_lshlrev_b32_e32 v4, 16, v5
	v_and_b32_e32 v5, 0xffff0000, v5
	v_pk_mul_f32 v[48:49], v[32:33], v[6:7]
	v_mul_f32_e32 v6, 0xbfb8aa3b, v4
	v_mul_f32_e32 v7, 0xbfb8aa3b, v5
	v_exp_f32_e32 v6, v6
	v_exp_f32_e32 v7, v7
	s_nop 0
	v_pk_add_f32 v[6:7], v[6:7], 1.0 op_sel_hi:[1,0]
	s_nop 0
	v_rcp_f32_e32 v25, v7
	s_nop 0
	v_fma_f32 v27, -v7, v25, 1.0
	v_fmac_f32_e32 v25, v27, v25
	v_div_fixup_f32 v7, v25, v7, 1.0
	v_rcp_f32_e32 v25, v6
	s_lshl_b32 s28, s33, 2
	s_add_u32 s28, s30, s28
	s_addc_u32 s29, s31, 0
	v_fma_f32 v27, -v6, v25, 1.0
	v_fmac_f32_e32 v25, v27, v25
	v_div_fixup_f32 v6, v25, v6, 1.0
	v_pk_mul_f32 v[32:33], v[6:7], v[4:5]
	v_lshlrev_b32_e32 v4, 2, v21
	v_mov_b32_e32 v5, v3
	v_lshl_add_u64 v[4:5], s[28:29], 0, v[4:5]
	v_lshl_add_u64 v[74:75], s[0:1], 2, v[4:5]
	global_load_dwordx4 v[4:7], v[74:75], off
	s_nop 0
	global_load_dwordx2 v[82:83], v[82:83], off offset:2048
	s_add_u32 s28, s22, s26
	global_load_dwordx2 v[78:79], v[78:79], off offset:2560
	s_addc_u32 s29, s23, s27
	v_lshl_add_u64 v[70:71], s[28:29], 0, v[2:3]
	global_load_dwordx2 v[76:77], v[76:77], off offset:3584
	s_mov_b32 s28, 0xc2480000
	s_mov_b32 s33, 0xc2fc0000
	v_and_or_b32 v21, v21, s83, v17
	v_lshlrev_b32_e32 v21, 2, v21
	s_waitcnt vmcnt(3)
	v_pk_add_f32 v[134:135], v[4:5], 1.0 op_sel_hi:[1,0] neg_lo:[1,0] neg_hi:[1,0]
	s_waitcnt vmcnt(2)
	v_lshlrev_b32_e32 v2, 16, v82
	v_mul_f32_e32 v2, 0xbfb8aa3b, v2
	v_exp_f32_e32 v2, v2
	v_and_b32_e32 v23, 0xffff0000, v82
	v_lshlrev_b32_e32 v25, 16, v83
	v_and_b32_e32 v82, 0xffff0000, v83
	v_add_f32_e32 v27, 1.0, v2
	v_rcp_f32_e32 v84, v27
	s_nop 0
	v_fma_f32 v85, -v27, v84, 1.0
	v_fmac_f32_e32 v84, v85, v84
	v_div_fixup_f32 v107, v84, v27, 1.0
	v_mul_f32_e32 v105, v2, v107
	v_mul_f32_e32 v2, 0xbfb8aa3b, v23
	v_exp_f32_e32 v2, v2
	v_fma_f32 v107, v134, v107, v4
	v_log_f32_e32 v107, v107
	v_mul_f32_e32 v154, v134, v105
	v_add_f32_e32 v23, 1.0, v2
	v_rcp_f32_e32 v83, v23
	v_max_f32_e32 v132, 0xc2c80000, v107
	v_fma_f32 v84, -v23, v83, 1.0
	v_fmac_f32_e32 v83, v84, v83
	v_div_fixup_f32 v108, v83, v23, 1.0
	v_mul_f32_e32 v106, v2, v108
	v_mul_f32_e32 v2, 0xbfb8aa3b, v25
	v_exp_f32_e32 v2, v2
	v_fma_f32 v105, v135, v108, v5
	v_log_f32_e32 v105, v105
	v_mul_f32_e32 v150, v135, v106
	v_add_f32_e32 v23, 1.0, v2
	v_rcp_f32_e32 v27, v23
	v_max_f32_e32 v124, 0xc2c80000, v105
	v_fma_f32 v83, -v23, v27, 1.0
	v_fmac_f32_e32 v27, v83, v27
	v_div_fixup_f32 v27, v27, v23, 1.0
	v_mul_f32_e32 v23, v2, v27
	v_mul_f32_e32 v2, 0xbfb8aa3b, v82
	v_exp_f32_e32 v2, v2
	s_nop 0
	v_add_f32_e32 v25, 1.0, v2
	v_rcp_f32_e32 v83, v25
	s_nop 0
	v_fma_f32 v84, -v25, v83, 1.0
	v_fmac_f32_e32 v83, v84, v83
	v_div_fixup_f32 v104, v83, v25, 1.0
	v_mul_f32_e32 v25, v2, v104
	s_waitcnt vmcnt(1)
	v_lshlrev_b32_e32 v2, 16, v78
	v_and_b32_e32 v78, 0xffff0000, v78
	v_mul_f32_e32 v2, 0xbfb8aa3b, v2
	v_lshlrev_b32_e32 v82, 16, v79
	v_exp_f32_e32 v86, v2
	v_mul_f32_e32 v2, 0xbfb8aa3b, v78
	v_and_b32_e32 v79, 0xffff0000, v79
	v_exp_f32_e32 v87, v2
	v_mul_f32_e32 v2, 0xbfb8aa3b, v82
	v_exp_f32_e32 v84, v2
	v_mul_f32_e32 v2, 0xbfb8aa3b, v79
	global_load_dwordx2 v[78:79], v[80:81], off offset:3072
	v_exp_f32_e32 v85, v2
	v_pk_add_f32 v[106:107], v[86:87], 1.0 op_sel_hi:[1,0]
	s_waitcnt vmcnt(0)
	v_lshlrev_b32_e32 v2, 16, v78
	v_mul_f32_e32 v2, 0xbfb8aa3b, v2
	v_exp_f32_e32 v2, v2
	v_and_b32_e32 v78, 0xffff0000, v78
	v_lshlrev_b32_e32 v80, 16, v79
	v_and_b32_e32 v79, 0xffff0000, v79
	v_add_f32_e32 v81, 1.0, v2
	v_rcp_f32_e32 v83, v81
	s_nop 0
	v_fma_f32 v88, -v81, v83, 1.0
	v_fmac_f32_e32 v83, v88, v83
	v_div_fixup_f32 v115, v83, v81, 1.0
	v_mul_f32_e32 v114, v2, v115
	v_mul_f32_e32 v2, 0xbfb8aa3b, v78
	v_exp_f32_e32 v2, v2
	v_mul_f32_e32 v152, v134, v114
	v_add_f32_e32 v78, 1.0, v2
	v_rcp_f32_e32 v82, v78
	s_nop 0
	v_fma_f32 v83, -v78, v82, 1.0
	v_fmac_f32_e32 v82, v83, v82
	v_div_fixup_f32 v116, v82, v78, 1.0
	v_mul_f32_e32 v110, v2, v116
	v_mul_f32_e32 v2, 0xbfb8aa3b, v80
	v_exp_f32_e32 v2, v2
	v_mul_f32_e32 v148, v135, v110
	v_add_f32_e32 v78, 1.0, v2
	v_rcp_f32_e32 v81, v78
	s_nop 0
	v_fma_f32 v82, -v78, v81, 1.0
	v_fmac_f32_e32 v81, v82, v81
	v_div_fixup_f32 v112, v81, v78, 1.0
	v_mul_f32_e32 v111, v2, v112
	v_mul_f32_e32 v2, 0xbfb8aa3b, v79
	v_exp_f32_e32 v2, v2
	s_nop 0
	v_add_f32_e32 v78, 1.0, v2
	v_rcp_f32_e32 v80, v78
	s_mov_b32 s26, 0x22000
	v_fma_f32 v81, -v78, v80, 1.0
	v_fmac_f32_e32 v80, v81, v80
	v_div_fixup_f32 v113, v80, v78, 1.0
	v_mul_f32_e32 v109, v2, v113
	v_lshlrev_b32_e32 v2, 16, v76
	v_and_b32_e32 v76, 0xffff0000, v76
	v_mul_f32_e32 v2, 0xbfb8aa3b, v2
	v_lshlrev_b32_e32 v78, 16, v77
	v_exp_f32_e32 v90, v2
	v_mul_f32_e32 v2, 0xbfb8aa3b, v76
	v_and_b32_e32 v77, 0xffff0000, v77
	v_exp_f32_e32 v91, v2
	v_mul_f32_e32 v2, 0xbfb8aa3b, v78
	v_add_co_u32_e32 v76, vcc, s26, v68
	v_exp_f32_e32 v88, v2
	v_mul_f32_e32 v2, 0xbfb8aa3b, v77
	v_addc_co_u32_e32 v77, vcc, 0, v69, vcc
	global_load_dwordx2 v[78:79], v[76:77], off
	v_exp_f32_e32 v89, v2
	s_waitcnt vmcnt(0)
	v_lshlrev_b32_e32 v2, 16, v78
	v_mul_f32_e32 v2, 0xbfb8aa3b, v2
	v_exp_f32_e32 v2, v2
	v_and_b32_e32 v78, 0xffff0000, v78
	v_lshlrev_b32_e32 v80, 16, v79
	v_and_b32_e32 v79, 0xffff0000, v79
	v_add_f32_e32 v81, 1.0, v2
	v_rcp_f32_e32 v83, v81
	s_nop 0
	v_fma_f32 v92, -v81, v83, 1.0
	v_fmac_f32_e32 v83, v92, v83
	v_div_fixup_f32 v123, v83, v81, 1.0
	v_mul_f32_e32 v122, v2, v123
	v_mul_f32_e32 v2, 0xbfb8aa3b, v78
	v_exp_f32_e32 v2, v2
	v_mul_f32_e32 v146, v134, v122
	v_add_f32_e32 v78, 1.0, v2
	v_rcp_f32_e32 v82, v78
	s_nop 0
	v_fma_f32 v83, -v78, v82, 1.0
	v_fmac_f32_e32 v82, v83, v82
	v_div_fixup_f32 v125, v82, v78, 1.0
	v_mul_f32_e32 v117, v2, v125
	v_mul_f32_e32 v2, 0xbfb8aa3b, v80
	v_exp_f32_e32 v2, v2
	v_mul_f32_e32 v144, v135, v117
	v_add_f32_e32 v78, 1.0, v2
	v_rcp_f32_e32 v81, v78
	s_nop 0
	v_fma_f32 v82, -v78, v81, 1.0
	v_fmac_f32_e32 v81, v82, v81
	v_div_fixup_f32 v120, v81, v78, 1.0
	v_mul_f32_e32 v119, v2, v120
	v_mul_f32_e32 v2, 0xbfb8aa3b, v79
	v_exp_f32_e32 v2, v2
	s_nop 0
	v_add_f32_e32 v78, 1.0, v2
	v_rcp_f32_e32 v80, v78
	s_mov_b32 s26, 0x2a000
	v_fma_f32 v81, -v78, v80, 1.0
	v_fmac_f32_e32 v80, v81, v80
	v_add_co_u32_e32 v82, vcc, s26, v68
	v_div_fixup_f32 v121, v80, v78, 1.0
	s_nop 0
	v_addc_co_u32_e32 v83, vcc, 0, v69, vcc
	global_load_dwordx2 v[78:79], v[82:83], off offset:512
	v_mul_f32_e32 v118, v2, v121
	s_mov_b32 s26, 0x32000
	s_waitcnt vmcnt(0)
	v_lshlrev_b32_e32 v2, 16, v78
	v_and_b32_e32 v78, 0xffff0000, v78
	v_mul_f32_e32 v2, 0xbfb8aa3b, v2
	v_lshlrev_b32_e32 v80, 16, v79
	v_exp_f32_e32 v100, v2
	v_mul_f32_e32 v2, 0xbfb8aa3b, v78
	v_exp_f32_e32 v101, v2
	v_mul_f32_e32 v2, 0xbfb8aa3b, v80
	v_add_co_u32_e32 v80, vcc, s26, v68
	v_and_b32_e32 v79, 0xffff0000, v79
	s_nop 0
	v_addc_co_u32_e32 v81, vcc, 0, v69, vcc
	v_exp_f32_e32 v98, v2
	v_mul_f32_e32 v2, 0xbfb8aa3b, v79
	global_load_dwordx2 v[78:79], v[80:81], off offset:1024
	v_exp_f32_e32 v99, v2
	s_waitcnt vmcnt(0)
	v_lshlrev_b32_e32 v2, 16, v78
	v_mul_f32_e32 v2, 0xbfb8aa3b, v2
	v_exp_f32_e32 v2, v2
	v_and_b32_e32 v78, 0xffff0000, v78
	v_lshlrev_b32_e32 v92, 16, v79
	v_and_b32_e32 v79, 0xffff0000, v79
	v_add_f32_e32 v93, 1.0, v2
	v_rcp_f32_e32 v95, v93
	s_nop 0
	v_fma_f32 v96, -v93, v95, 1.0
	v_fmac_f32_e32 v95, v96, v95
	v_div_fixup_f32 v139, v95, v93, 1.0
	v_mul_f32_e32 v138, v2, v139
	v_mul_f32_e32 v2, 0xbfb8aa3b, v78
	v_exp_f32_e32 v2, v2
	v_mul_f32_e32 v142, v134, v138
	v_add_f32_e32 v78, 1.0, v2
	v_rcp_f32_e32 v94, v78
	s_nop 0
	v_fma_f32 v95, -v78, v94, 1.0
	v_fmac_f32_e32 v94, v95, v94
	v_div_fixup_f32 v140, v94, v78, 1.0
	v_mul_f32_e32 v133, v2, v140
	v_mul_f32_e32 v2, 0xbfb8aa3b, v92
	v_exp_f32_e32 v2, v2
	s_nop 0
	v_add_f32_e32 v78, 1.0, v2
	v_rcp_f32_e32 v93, v78
	s_nop 0
	v_fma_f32 v94, -v78, v93, 1.0
	v_fmac_f32_e32 v93, v94, v93
	v_div_fixup_f32 v128, v93, v78, 1.0
	v_mul_f32_e32 v127, v2, v128
	v_mul_f32_e32 v2, 0xbfb8aa3b, v79
	v_exp_f32_e32 v2, v2
	s_nop 0
	v_add_f32_e32 v78, 1.0, v2
	v_rcp_f32_e32 v92, v78
	s_mov_b32 s26, 0x3a000
	v_fma_f32 v93, -v78, v92, 1.0
	v_fmac_f32_e32 v92, v93, v92
	v_div_fixup_f32 v129, v92, v78, 1.0
	v_add_co_u32_e32 v78, vcc, s26, v68
	v_mul_f32_e32 v126, v2, v129
	s_nop 0
	v_addc_co_u32_e32 v79, vcc, 0, v69, vcc
	global_load_dwordx2 v[92:93], v[78:79], off offset:1536
	s_mov_b64 s[26:27], 0x3000000
	s_waitcnt vmcnt(0)
	v_lshlrev_b32_e32 v2, 16, v92
	v_and_b32_e32 v92, 0xffff0000, v92
	v_mul_f32_e32 v2, 0xbfb8aa3b, v2
	v_lshlrev_b32_e32 v94, 16, v93
	v_exp_f32_e32 v136, v2
	v_mul_f32_e32 v2, 0xbfb8aa3b, v92
	v_exp_f32_e32 v137, v2
	v_mul_f32_e32 v2, 0xbfb8aa3b, v94
	v_lshl_add_u64 v[94:95], v[70:71], 0, s[26:27]
	v_rcp_f32_e32 v108, v107
	v_pk_add_f32 v[168:169], v[136:137], 1.0 op_sel_hi:[1,0]
	v_and_b32_e32 v93, 0xffff0000, v93
	v_exp_f32_e32 v102, v2
	v_fma_f32 v130, -v107, v108, 1.0
	v_fmac_f32_e32 v108, v130, v108
	v_div_fixup_f32 v107, v108, v107, 1.0
	v_rcp_f32_e32 v108, v106
	v_mul_f32_e32 v2, 0xbfb8aa3b, v93
	v_exp_f32_e32 v103, v2
	v_lshlrev_b32_e32 v2, 1, v12
	v_fma_f32 v130, -v106, v108, 1.0
	v_fmac_f32_e32 v108, v130, v108
	v_div_fixup_f32 v106, v108, v106, 1.0
	v_pk_mul_f32 v[130:131], v[134:135], v[106:107]
	v_pk_mul_f32 v[86:87], v[86:87], v[106:107]
	v_fma_f32 v106, v134, v123, v4
	v_log_f32_e32 v106, v106
	v_add_f32_e32 v105, v4, v130
	v_add_f32_e32 v108, v5, v131
	v_log_f32_e32 v105, v105
	v_max_f32_e32 v141, 0xc2c80000, v106
	v_fma_f32 v106, v135, v125, v5
	v_log_f32_e32 v106, v106
	v_log_f32_e32 v108, v108
	v_pk_mul_f32 v[130:131], v[134:135], v[86:87]
	v_fma_f32 v86, v134, v115, v4
	v_max_f32_e32 v162, 0xc2c80000, v106
	v_fma_f32 v106, v134, v139, v4
	v_log_f32_e32 v106, v106
	v_fma_f32 v87, v135, v116, v5
	v_log_f32_e32 v86, v86
	v_log_f32_e32 v87, v87
	v_pk_add_f32 v[116:117], v[6:7], 1.0 op_sel_hi:[1,0] neg_lo:[1,0] neg_hi:[1,0]
	v_max_f32_e32 v122, 0xc2c80000, v106
	v_fma_f32 v106, v135, v140, v5
	v_mul_f32_e32 v151, v116, v23
	v_fma_f32 v23, v117, v104, v7
	v_log_f32_e32 v106, v106
	v_log_f32_e32 v23, v23
	v_max_f32_e32 v105, 0xc2c80000, v105
	v_max_f32_e32 v108, 0xc2c80000, v108
	v_max_f32_e32 v86, 0xc2c80000, v86
	v_max_f32_e32 v87, 0xc2c80000, v87
	v_add_f32_e32 v161, v132, v105
	v_add_f32_e32 v160, v124, v108
	v_add_f32_e32 v158, v161, v86
	v_add_f32_e32 v156, v160, v87
	v_pk_add_f32 v[86:87], v[84:85], 1.0 op_sel_hi:[1,0]
	v_max_f32_e32 v123, 0xc2c80000, v106
	v_fma_f32 v27, v116, v27, v6
	v_max_f32_e32 v106, 0xc2c80000, v23
	v_log_f32_e32 v27, v27
	v_mul_f32_e32 v147, v117, v25
	v_rcp_f32_e32 v25, v87
	v_mul_f32_e32 v149, v116, v111
	v_max_f32_e32 v110, 0xc2c80000, v27
	v_mul_f32_e32 v143, v116, v119
	v_fma_f32 v27, -v87, v25, 1.0
	v_fmac_f32_e32 v25, v27, v25
	v_div_fixup_f32 v87, v25, v87, 1.0
	v_rcp_f32_e32 v25, v86
	v_mul_f32_e32 v107, v135, v133
	v_mul_f32_e32 v145, v117, v109
	v_lshl_add_u64 v[96:97], v[94:95], 0, v[2:3]
	v_fma_f32 v27, -v86, v25, 1.0
	v_fmac_f32_e32 v25, v27, v25
	v_div_fixup_f32 v86, v25, v86, 1.0
	v_pk_mul_f32 v[104:105], v[116:117], v[86:87]
	v_pk_mul_f32 v[84:85], v[84:85], v[86:87]
	v_add_f32_e32 v23, v6, v104
	v_log_f32_e32 v23, v23
	v_mul_f32_e32 v27, v117, v118
	v_mul_f32_e32 v25, v116, v127
	v_lshlrev_b32_e32 v86, 1, v16
	v_max_f32_e32 v108, 0xc2c80000, v23
	v_add_f32_e32 v23, v7, v105
	v_log_f32_e32 v23, v23
	v_pk_mul_f32 v[104:105], v[116:117], v[84:85]
	v_add_f32_e32 v159, v110, v108
	v_mov_b32_e32 v87, v3
	v_max_f32_e32 v114, 0xc2c80000, v23
	v_fma_f32 v23, v116, v112, v6
	v_log_f32_e32 v23, v23
	v_add_f32_e32 v157, v106, v114
	v_pk_add_f32 v[114:115], v[90:91], 1.0 op_sel_hi:[1,0]
	v_lshl_add_u64 v[108:109], v[94:95], 0, v[86:87]
	v_max_f32_e32 v84, 0xc2c80000, v23
	v_fma_f32 v23, v117, v113, v7
	v_log_f32_e32 v23, v23
	v_div_scale_f32 v111, s[26:27], v115, v115, 1.0
	v_rcp_f32_e32 v118, v111
	v_max_f32_e32 v85, 0xc2c80000, v23
	v_fma_f32 v23, v116, v120, v6
	v_log_f32_e32 v23, v23
	v_fma_f32 v119, -v111, v118, 1.0
	v_fmac_f32_e32 v118, v119, v118
	v_div_scale_f32 v119, vcc, 1.0, v115, 1.0
	v_max_f32_e32 v120, 0xc2c80000, v23
	v_fma_f32 v23, v117, v121, v7
	v_log_f32_e32 v23, v23
	v_add_f32_e32 v155, v159, v84
	v_add_f32_e32 v153, v157, v85
	v_lshlrev_b32_e32 v84, 1, v14
	v_max_f32_e32 v121, 0xc2c80000, v23
	v_fma_f32 v23, v116, v128, v6
	v_log_f32_e32 v23, v23
	v_mov_b32_e32 v85, v3
	v_lshl_add_u64 v[112:113], v[94:95], 0, v[84:85]
	v_lshl_add_u64 v[92:93], v[70:71], 0, v[2:3]
	v_max_f32_e32 v125, 0xc2c80000, v23
	v_fma_f32 v23, v117, v129, v7
	v_log_f32_e32 v23, v23
	s_nop 0
	v_max_f32_e32 v133, 0xc2c80000, v23
	v_mul_f32_e32 v23, v117, v126
	v_mul_f32_e32 v126, v119, v118
	v_fma_f32 v127, -v111, v126, v119
	v_fmac_f32_e32 v126, v127, v118
	v_fma_f32 v111, -v111, v126, v119
	v_div_fmas_f32 v111, v111, v118, v126
	v_div_fixup_f32 v115, v111, v115, 1.0
	v_rcp_f32_e32 v118, v114
	s_nop 0
	v_fma_f32 v119, -v114, v118, 1.0
	v_fmac_f32_e32 v118, v119, v118
	v_div_fixup_f32 v114, v118, v114, 1.0
	v_pk_mul_f32 v[90:91], v[90:91], v[114:115]
	v_pk_mul_f32 v[114:115], v[134:135], v[114:115]
	v_pk_mul_f32 v[138:139], v[134:135], v[90:91]
	v_add_f32_e32 v111, v4, v114
	v_add_f32_e32 v114, v5, v115
	v_log_f32_e32 v114, v114
	v_pk_add_f32 v[90:91], v[88:89], 1.0 op_sel_hi:[1,0]
	v_log_f32_e32 v111, v111
	v_max_f32_e32 v114, 0xc2c80000, v114
	v_add_f32_e32 v165, v156, v114
	v_rcp_f32_e32 v115, v91
	v_max_f32_e32 v111, 0xc2c80000, v111
	v_add_f32_e32 v192, v158, v111
	v_add_f32_e32 v163, v192, v141
	v_fma_f32 v118, -v91, v115, 1.0
	v_fmac_f32_e32 v115, v118, v115
	v_div_fixup_f32 v91, v115, v91, 1.0
	v_rcp_f32_e32 v115, v90
	v_add_f32_e32 v111, v165, v162
	v_fma_f32 v118, -v90, v115, 1.0
	v_fmac_f32_e32 v115, v118, v115
	v_pk_add_f32 v[126:127], v[100:101], 1.0 op_sel_hi:[1,0]
	v_rcp_f32_e32 v129, v127
	v_div_fixup_f32 v90, v115, v90, 1.0
	v_pk_mul_f32 v[88:89], v[88:89], v[90:91]
	v_fma_f32 v140, -v127, v129, 1.0
	v_fmac_f32_e32 v129, v140, v129
	v_div_fixup_f32 v127, v129, v127, 1.0
	v_rcp_f32_e32 v129, v126
	v_pk_mul_f32 v[90:91], v[116:117], v[90:91]
	v_pk_mul_f32 v[118:119], v[116:117], v[88:89]
	v_add_f32_e32 v90, v6, v90
	v_fma_f32 v140, -v126, v129, 1.0
	v_fmac_f32_e32 v129, v140, v129
	v_div_fixup_f32 v126, v129, v126, 1.0
	v_pk_mul_f32 v[100:101], v[100:101], v[126:127]
	v_pk_mul_f32 v[126:127], v[134:135], v[126:127]
	v_pk_mul_f32 v[140:141], v[134:135], v[100:101]
	v_add_f32_e32 v126, v4, v126
	v_log_f32_e32 v126, v126
	v_add_f32_e32 v127, v5, v127
	v_log_f32_e32 v127, v127
	v_pk_add_f32 v[100:101], v[98:99], 1.0 op_sel_hi:[1,0]
	v_max_f32_e32 v126, 0xc2c80000, v126
	v_add_f32_e32 v196, v163, v126
	v_max_f32_e32 v127, 0xc2c80000, v127
	v_add_f32_e32 v195, v111, v127
	v_add_f32_e32 v194, v196, v122
	v_add_f32_e32 v167, v195, v123
	v_rcp_f32_e32 v123, v101
	v_log_f32_e32 v90, v90
	v_add_f32_e32 v91, v7, v91
	v_log_f32_e32 v91, v91
	v_fma_f32 v126, -v101, v123, 1.0
	v_fmac_f32_e32 v123, v126, v123
	v_div_fixup_f32 v101, v123, v101, 1.0
	v_rcp_f32_e32 v123, v100
	v_max_f32_e32 v90, 0xc2c80000, v90
	v_max_f32_e32 v91, 0xc2c80000, v91
	v_add_f32_e32 v186, v155, v90
	v_fma_f32 v126, -v100, v123, 1.0
	v_fmac_f32_e32 v123, v126, v123
	v_div_fixup_f32 v100, v123, v100, 1.0
	v_pk_mul_f32 v[98:99], v[98:99], v[100:101]
	v_pk_mul_f32 v[100:101], v[116:117], v[100:101]
	v_add_f32_e32 v183, v153, v91
	v_add_f32_e32 v100, v6, v100
	v_log_f32_e32 v100, v100
	v_add_f32_e32 v101, v7, v101
	v_log_f32_e32 v101, v101
	v_add_f32_e32 v178, v186, v120
	v_max_f32_e32 v100, 0xc2c80000, v100
	v_add_f32_e32 v172, v183, v121
	v_max_f32_e32 v101, 0xc2c80000, v101
	v_add_f32_e32 v189, v178, v100
	v_add_f32_e32 v188, v172, v101
	v_add_f32_e32 v187, v189, v125
	v_add_f32_e32 v184, v188, v133
	v_rcp_f32_e32 v133, v169
	v_pk_mul_f32 v[128:129], v[116:117], v[98:99]
	v_lshlrev_b32_e32 v90, 1, v20
	v_mov_b32_e32 v91, v3
	v_fma_f32 v162, -v169, v133, 1.0
	v_fmac_f32_e32 v133, v162, v133
	v_div_fixup_f32 v169, v133, v169, 1.0
	v_rcp_f32_e32 v133, v168
	v_lshlrev_b32_e32 v88, 1, v18
	v_mov_b32_e32 v89, v3
	v_lshl_add_u64 v[114:115], v[94:95], 0, v[90:91]
	v_fma_f32 v162, -v168, v133, 1.0
	v_fmac_f32_e32 v133, v162, v133
	v_div_fixup_f32 v168, v133, v168, 1.0
	v_pk_mul_f32 v[136:137], v[136:137], v[168:169]
	v_pk_mul_f32 v[168:169], v[134:135], v[168:169]
	v_pk_mul_f32 v[136:137], v[134:135], v[136:137]
	v_add_f32_e32 v4, v4, v168
	v_log_f32_e32 v4, v4
	v_add_f32_e32 v5, v5, v169
	v_log_f32_e32 v5, v5
	v_lshlrev_b32_e32 v98, 1, v22
	v_max_f32_e32 v4, 0xc2c80000, v4
	v_add_f32_e32 v173, v194, v4
	ds_bpermute_b32 v176, v13, v173
	ds_bpermute_b32 v177, v15, v173
	ds_bpermute_b32 v174, v9, v173
	v_max_f32_e32 v5, 0xc2c80000, v5
	v_add_f32_e32 v175, v167, v5
	ds_bpermute_b32 v181, v13, v175
	s_waitcnt lgkmcnt(2)
	v_cndmask_b32_e64 v4, v177, v176, s[4:5]
	s_waitcnt lgkmcnt(1)
	v_cndmask_b32_e64 v4, v4, v174, s[10:11]
	v_cndmask_b32_e64 v179, v4, v173, s[8:9]
	v_cndmask_b32_e64 v4, v177, v176, s[10:11]
	v_cndmask_b32_e64 v4, v4, v174, s[4:5]
	ds_bpermute_b32 v182, v15, v175
	v_cndmask_b32_e64 v169, v4, v173, s[6:7]
	v_cndmask_b32_e64 v4, v177, v176, s[8:9]
	ds_bpermute_b32 v180, v9, v175
	v_cndmask_b32_e64 v4, v4, v174, s[6:7]
	v_cndmask_b32_e64 v133, v4, v173, s[4:5]
	v_cndmask_b32_e64 v4, v4, 0, s[4:5]
	v_cndmask_b32_e64 v5, 0, v169, s[16:17]
	v_add_f32_e32 v4, v4, v5
	v_cndmask_b32_e64 v5, 0, v179, s[18:19]
	v_add_f32_e32 v168, v5, v4
	s_waitcnt lgkmcnt(1)
	v_cndmask_b32_e64 v4, v182, v181, s[4:5]
	s_waitcnt lgkmcnt(0)
	v_cndmask_b32_e64 v4, v4, v180, s[10:11]
	v_cndmask_b32_e64 v185, v4, v175, s[8:9]
	v_cndmask_b32_e64 v4, v182, v181, s[10:11]
	v_cndmask_b32_e64 v4, v4, v180, s[4:5]
	v_cndmask_b32_e64 v171, v4, v175, s[6:7]
	v_cndmask_b32_e64 v4, v182, v181, s[8:9]
	v_cndmask_b32_e64 v4, v4, v180, s[6:7]
	v_cndmask_b32_e64 v125, v4, v175, s[4:5]
	v_cndmask_b32_e64 v4, v4, 0, s[4:5]
	v_cndmask_b32_e64 v5, 0, v171, s[16:17]
	v_add_f32_e32 v4, v4, v5
	v_cndmask_b32_e64 v5, 0, v185, s[18:19]
	v_add_f32_e32 v170, v5, v4
	v_pk_add_f32 v[4:5], v[132:133], v[168:169]
	v_pk_add_f32 v[124:125], v[124:125], v[170:171]
	v_sub_f32_e32 v132, v4, v5
	v_med3_f32 v132, v132, s28, v236
	v_sub_f32_e32 v4, v5, v4
	v_med3_f32 v4, v4, s28, v236
	v_exp_f32_e32 v132, v132
	v_add_f32_e32 v135, v160, v170
	v_exp_f32_e32 v4, v4
	v_add_f32_e32 v111, v111, v170
	v_mov_b32_e32 v99, v3
	v_sub_f32_e32 v133, v124, v125
	v_med3_f32 v133, v133, s28, v236
	v_sub_f32_e32 v124, v125, v124
	v_med3_f32 v124, v124, s28, v236
	v_exp_f32_e32 v133, v133
	v_mul_f32_e32 v4, v154, v4
	v_pk_mul_f32 v[132:133], v[46:47], v[132:133]
	v_exp_f32_e32 v124, v124
	v_cvt_pk_bf16_f32 v166, v132, v133
	v_add_f32_e32 v133, v161, v168
	v_sub_f32_e32 v132, v133, v5
	v_med3_f32 v132, v132, s28, v236
	v_sub_f32_e32 v133, v5, v133
	v_exp_f32_e32 v132, v132
	v_med3_f32 v133, v133, s28, v236
	v_mul_f32_e32 v124, v150, v124
	s_nop 1
	v_exp_f32_e32 v133, v133
	v_cvt_pk_bf16_f32 v164, v4, v124
	v_lshlrev_b32_e32 v100, 1, v24
	v_mov_b32_e32 v134, v133
	v_sub_f32_e32 v133, v135, v125
	v_med3_f32 v133, v133, s28, v236
	v_sub_f32_e32 v135, v125, v135
	v_med3_f32 v135, v135, s28, v236
	v_exp_f32_e32 v133, v133
	v_mov_b32_e32 v101, v3
	v_pk_mul_f32 v[132:133], v[44:45], v[132:133]
	v_exp_f32_e32 v135, v135
	v_cvt_pk_bf16_f32 v162, v132, v133
	v_add_f32_e32 v133, v158, v168
	v_sub_f32_e32 v132, v133, v5
	v_med3_f32 v132, v132, s28, v236
	v_pk_mul_f32 v[130:131], v[130:131], v[134:135]
	v_sub_f32_e32 v133, v5, v133
	v_exp_f32_e32 v132, v132
	v_med3_f32 v133, v133, s28, v236
	v_cvt_pk_bf16_f32 v160, v130, v131
	v_exp_f32_e32 v133, v133
	v_lshl_add_u64 v[120:121], v[94:95], 0, v[88:89]
	v_lshl_add_u64 v[126:127], v[94:95], 0, v[98:99]
	v_add_f32_e32 v134, v156, v170
	v_mul_f32_e32 v190, v152, v133
	v_sub_f32_e32 v133, v134, v125
	v_med3_f32 v133, v133, s28, v236
	v_sub_f32_e32 v134, v125, v134
	v_med3_f32 v134, v134, s28, v236
	v_exp_f32_e32 v133, v133
	v_lshl_add_u64 v[122:123], v[94:95], 0, v[100:101]
	v_pk_mul_f32 v[132:133], v[58:59], v[132:133]
	v_exp_f32_e32 v134, v134
	v_cvt_pk_bf16_f32 v158, v132, v133
	v_add_f32_e32 v133, v192, v168
	v_sub_f32_e32 v132, v133, v5
	v_med3_f32 v132, v132, s28, v236
	v_mul_f32_e32 v191, v148, v134
	v_sub_f32_e32 v133, v5, v133
	v_exp_f32_e32 v132, v132
	v_med3_f32 v133, v133, s28, v236
	v_add_f32_e32 v135, v165, v170
	s_nop 1
	v_exp_f32_e32 v133, v133
	v_cvt_pk_bf16_f32 v156, v190, v191
	v_mov_b32_e32 v134, v133
	v_sub_f32_e32 v133, v135, v125
	v_med3_f32 v133, v133, s28, v236
	s_nop 1
	v_exp_f32_e32 v133, v133
	s_nop 0
	v_pk_mul_f32 v[192:193], v[56:57], v[132:133]
	v_sub_f32_e32 v132, v125, v135
	v_med3_f32 v132, v132, s28, v236
	v_cvt_pk_bf16_f32 v154, v192, v193
	s_nop 0
	v_exp_f32_e32 v132, v132
	s_nop 0
	v_mov_b32_e32 v135, v132
	v_pk_mul_f32 v[132:133], v[138:139], v[134:135]
	v_add_f32_e32 v135, v163, v168
	v_sub_f32_e32 v134, v135, v5
	v_med3_f32 v134, v134, s28, v236
	v_sub_f32_e32 v135, v5, v135
	v_med3_f32 v135, v135, s28, v236
	v_exp_f32_e32 v134, v134
	v_cvt_pk_bf16_f32 v152, v132, v133
	v_exp_f32_e32 v135, v135
	s_nop 0
	v_mul_f32_e32 v192, v146, v135
	v_sub_f32_e32 v135, v111, v125
	v_med3_f32 v135, v135, s28, v236
	v_sub_f32_e32 v111, v125, v111
	v_med3_f32 v111, v111, s28, v236
	v_exp_f32_e32 v135, v135
	s_nop 0
	v_exp_f32_e32 v111, v111
	v_pk_mul_f32 v[134:135], v[54:55], v[134:135]
	v_mul_f32_e32 v193, v144, v111
	v_add_f32_e32 v111, v196, v168
	v_cvt_pk_bf16_f32 v150, v134, v135
	v_sub_f32_e32 v134, v111, v5
	v_med3_f32 v134, v134, s28, v236
	v_sub_f32_e32 v111, v5, v111
	v_med3_f32 v111, v111, s28, v236
	v_exp_f32_e32 v134, v134
	v_cvt_pk_bf16_f32 v148, v192, v193
	s_nop 1
	v_exp_f32_e32 v111, v111
	s_nop 0
	v_mov_b32_e32 v138, v111
	v_add_f32_e32 v111, v195, v170
	v_sub_f32_e32 v135, v111, v125
	v_med3_f32 v135, v135, s28, v236
	v_sub_f32_e32 v111, v125, v111
	v_med3_f32 v111, v111, s28, v236
	v_exp_f32_e32 v135, v135
	s_nop 0
	v_pk_mul_f32 v[196:197], v[52:53], v[134:135]
	s_nop 1
	v_exp_f32_e32 v111, v111
	v_cvt_pk_bf16_f32 v146, v196, v197
	v_mov_b32_e32 v139, v111
	v_add_f32_e32 v111, v194, v168
	v_pk_mul_f32 v[134:135], v[140:141], v[138:139]
	v_sub_f32_e32 v138, v111, v5
	v_med3_f32 v138, v138, s28, v236
	v_sub_f32_e32 v111, v5, v111
	v_med3_f32 v111, v111, s28, v236
	v_exp_f32_e32 v138, v138
	v_cvt_pk_bf16_f32 v144, v134, v135
	v_exp_f32_e32 v111, v111
	s_nop 0
	v_mul_f32_e32 v194, v142, v111
	v_add_f32_e32 v111, v167, v170
	v_sub_f32_e32 v139, v111, v125
	v_med3_f32 v139, v139, s28, v236
	v_sub_f32_e32 v111, v125, v111
	v_med3_f32 v111, v111, s28, v236
	v_exp_f32_e32 v139, v139
	s_nop 0
	v_exp_f32_e32 v111, v111
	v_pk_mul_f32 v[138:139], v[50:51], v[138:139]
	v_mul_f32_e32 v195, v107, v111
	v_add_f32_e32 v107, v173, v168
	v_sub_f32_e32 v111, v107, v5
	v_med3_f32 v111, v111, s28, v236
	v_cvt_pk_bf16_f32 v142, v138, v139
	v_sub_f32_e32 v107, v5, v107
	v_exp_f32_e32 v111, v111
	v_med3_f32 v107, v107, s28, v236
	v_mov_b32_e32 v138, v111
	v_cvt_pk_bf16_f32 v140, v194, v195
	v_exp_f32_e32 v107, v107
	s_nop 0
	v_mov_b32_e32 v168, v107
	v_add_f32_e32 v107, v175, v170
	v_sub_f32_e32 v111, v107, v125
	v_med3_f32 v111, v111, s28, v236
	v_sub_f32_e32 v107, v125, v107
	v_med3_f32 v107, v107, s28, v236
	v_exp_f32_e32 v111, v111
	s_nop 0
	v_mov_b32_e32 v139, v111
	s_nop 0
	v_exp_f32_e32 v107, v107
	v_pk_mul_f32 v[138:139], v[48:49], v[138:139]
	v_mov_b32_e32 v169, v107
	v_pk_mul_f32 v[136:137], v[136:137], v[168:169]
	v_pk_add_f32 v[168:169], v[102:103], 1.0 op_sel_hi:[1,0]
	s_nop 0
	v_rcp_f32_e32 v111, v169
	s_nop 0
	v_fma_f32 v141, -v169, v111, 1.0
	v_fmac_f32_e32 v111, v141, v111
	v_div_fixup_f32 v169, v111, v169, 1.0
	v_rcp_f32_e32 v111, v168
	s_mov_b64 s[26:27], 0x6000000
	v_fma_f32 v141, -v168, v111, 1.0
	v_fmac_f32_e32 v111, v141, v111
	v_div_fixup_f32 v168, v111, v168, 1.0
	v_pk_mul_f32 v[102:103], v[102:103], v[168:169]
	v_pk_mul_f32 v[168:169], v[116:117], v[168:169]
	v_pk_mul_f32 v[116:117], v[116:117], v[102:103]
	v_add_f32_e32 v6, v6, v168
	v_log_f32_e32 v6, v6
	v_add_f32_e32 v7, v7, v169
	v_log_f32_e32 v7, v7
	v_max_f32_e32 v6, 0xc2c80000, v6
	v_add_f32_e32 v196, v187, v6
	ds_bpermute_b32 v201, v13, v196
	ds_bpermute_b32 v202, v15, v196
	ds_bpermute_b32 v197, v9, v196
	v_max_f32_e32 v7, 0xc2c80000, v7
	v_add_f32_e32 v200, v184, v7
	ds_bpermute_b32 v205, v13, v200
	s_waitcnt lgkmcnt(2)
	v_cndmask_b32_e64 v6, v202, v201, s[4:5]
	s_waitcnt lgkmcnt(1)
	v_cndmask_b32_e64 v6, v6, v197, s[10:11]
	v_cndmask_b32_e64 v203, v6, v196, s[8:9]
	v_cndmask_b32_e64 v6, v202, v201, s[10:11]
	v_cndmask_b32_e64 v6, v6, v197, s[4:5]
	ds_bpermute_b32 v206, v15, v200
	v_cndmask_b32_e64 v169, v6, v196, s[6:7]
	v_cndmask_b32_e64 v6, v202, v201, s[8:9]
	ds_bpermute_b32 v204, v9, v200
	v_cndmask_b32_e64 v6, v6, v197, s[6:7]
	v_cndmask_b32_e64 v111, v6, v196, s[4:5]
	v_cndmask_b32_e64 v6, v6, 0, s[4:5]
	v_cndmask_b32_e64 v7, 0, v169, s[16:17]
	v_add_f32_e32 v6, v6, v7
	v_cndmask_b32_e64 v7, 0, v203, s[18:19]
	v_add_f32_e32 v168, v7, v6
	s_waitcnt lgkmcnt(1)
	v_cndmask_b32_e64 v6, v206, v205, s[4:5]
	s_waitcnt lgkmcnt(0)
	v_cndmask_b32_e64 v6, v6, v204, s[10:11]
	v_cndmask_b32_e64 v207, v6, v200, s[8:9]
	v_cndmask_b32_e64 v6, v206, v205, s[10:11]
	v_cndmask_b32_e64 v6, v6, v204, s[4:5]
	v_cndmask_b32_e64 v171, v6, v200, s[6:7]
	v_cndmask_b32_e64 v6, v206, v205, s[8:9]
	v_cndmask_b32_e64 v6, v6, v204, s[6:7]
	v_cndmask_b32_e64 v107, v6, v200, s[4:5]
	v_cndmask_b32_e64 v6, v6, 0, s[4:5]
	v_cndmask_b32_e64 v102, 0, v171, s[16:17]
	v_cndmask_b32_e64 v7, 0, v207, s[18:19]
	v_add_f32_e32 v6, v6, v102
	v_add_f32_e32 v170, v7, v6
	v_pk_add_f32 v[6:7], v[110:111], v[168:169]
	s_nop 0
	v_sub_f32_e32 v102, v6, v7
	v_med3_f32 v102, v102, s28, v236
	v_sub_f32_e32 v6, v7, v6
	v_med3_f32 v6, v6, s28, v236
	v_exp_f32_e32 v102, v102
	s_nop 0
	v_mov_b32_e32 v110, v102
	s_nop 0
	v_exp_f32_e32 v6, v6
	v_pk_add_f32 v[102:103], v[106:107], v[170:171]
	v_mul_f32_e32 v6, v151, v6
	v_sub_f32_e32 v106, v102, v103
	v_med3_f32 v106, v106, s28, v236
	v_sub_f32_e32 v102, v103, v102
	v_med3_f32 v102, v102, s28, v236
	v_exp_f32_e32 v106, v106
	s_nop 0
	v_mov_b32_e32 v111, v106
	v_pk_mul_f32 v[106:107], v[30:31], v[110:111]
	v_exp_f32_e32 v102, v102
	v_cvt_pk_bf16_f32 v167, v106, v107
	v_add_f32_e32 v107, v157, v170
	v_mul_f32_e32 v102, v147, v102
	v_cvt_pk_bf16_f32 v165, v6, v102
	global_store_dwordx2 v[96:97], v[164:165], off
	v_add_f32_e32 v97, v159, v168
	v_sub_f32_e32 v96, v97, v7
	v_med3_f32 v96, v96, s28, v236
	v_sub_f32_e32 v97, v7, v97
	v_med3_f32 v97, v97, s28, v236
	v_exp_f32_e32 v96, v96
	global_store_dwordx2 v[92:93], v[166:167], off
	s_nop 1
	v_exp_f32_e32 v97, v97
	s_nop 0
	v_mov_b32_e32 v106, v97
	v_sub_f32_e32 v97, v107, v103
	v_med3_f32 v97, v97, s28, v236
	s_nop 1
	v_exp_f32_e32 v97, v97
	s_nop 0
	v_pk_mul_f32 v[110:111], v[28:29], v[96:97]
	v_sub_f32_e32 v96, v103, v107
	v_med3_f32 v96, v96, s28, v236
	v_cvt_pk_bf16_f32 v163, v110, v111
	global_store_dwordx2 v[92:93], v[162:163], off offset:256
	v_exp_f32_e32 v96, v96
	s_nop 0
	v_mov_b32_e32 v107, v96
	v_pk_mul_f32 v[96:97], v[104:105], v[106:107]
	v_add_f32_e32 v105, v155, v168
	v_sub_f32_e32 v104, v105, v7
	v_med3_f32 v104, v104, s28, v236
	v_sub_f32_e32 v105, v7, v105
	v_med3_f32 v105, v105, s28, v236
	v_exp_f32_e32 v104, v104
	v_cvt_pk_bf16_f32 v161, v96, v97
	v_exp_f32_e32 v105, v105
	global_store_dwordx2 v[112:113], v[160:161], off
	v_add_f32_e32 v106, v153, v170
	v_mul_f32_e32 v160, v149, v105
	v_sub_f32_e32 v105, v106, v103
	v_med3_f32 v105, v105, s28, v236
	v_sub_f32_e32 v106, v103, v106
	v_med3_f32 v106, v106, s28, v236
	v_exp_f32_e32 v105, v105
	s_nop 0
	v_pk_mul_f32 v[104:105], v[42:43], v[104:105]
	v_exp_f32_e32 v106, v106
	v_cvt_pk_bf16_f32 v159, v104, v105
	v_add_f32_e32 v105, v186, v168
	v_sub_f32_e32 v104, v105, v7
	v_med3_f32 v104, v104, s28, v236
	v_mul_f32_e32 v161, v145, v106
	v_sub_f32_e32 v105, v7, v105
	v_exp_f32_e32 v104, v104
	v_med3_f32 v105, v105, s28, v236
	v_add_f32_e32 v107, v183, v170
	s_nop 1
	v_exp_f32_e32 v105, v105
	v_cvt_pk_bf16_f32 v157, v160, v161
	global_store_dwordx2 v[108:109], v[156:157], off
	v_mov_b32_e32 v106, v105
	v_sub_f32_e32 v105, v107, v103
	v_med3_f32 v105, v105, s28, v236
	global_store_dwordx2 v[92:93], v[158:159], off offset:512
	s_nop 0
	v_exp_f32_e32 v105, v105
	s_nop 0
	v_pk_mul_f32 v[108:109], v[40:41], v[104:105]
	v_sub_f32_e32 v104, v103, v107
	v_med3_f32 v104, v104, s28, v236
	v_cvt_pk_bf16_f32 v155, v108, v109
	global_store_dwordx2 v[92:93], v[154:155], off offset:768
	v_exp_f32_e32 v104, v104
	s_nop 0
	v_mov_b32_e32 v107, v104
	v_pk_mul_f32 v[104:105], v[118:119], v[106:107]
	v_add_f32_e32 v107, v178, v168
	v_sub_f32_e32 v106, v107, v7
	v_med3_f32 v106, v106, s28, v236
	v_sub_f32_e32 v107, v7, v107
	v_med3_f32 v107, v107, s28, v236
	v_exp_f32_e32 v106, v106
	v_cvt_pk_bf16_f32 v153, v104, v105
	v_exp_f32_e32 v107, v107
	v_cvt_pk_bf16_f32 v105, v161, v105
	global_store_dwordx2 v[120:121], v[152:153], off
	v_add_f32_e32 v108, v172, v170
	v_mul_f32_e32 v118, v143, v107
	v_sub_f32_e32 v107, v108, v103
	v_med3_f32 v107, v107, s28, v236
	v_sub_f32_e32 v108, v103, v108
	v_med3_f32 v108, v108, s28, v236
	v_exp_f32_e32 v107, v107
	s_nop 0
	v_pk_mul_f32 v[106:107], v[38:39], v[106:107]
	v_exp_f32_e32 v108, v108
	v_cvt_pk_bf16_f32 v151, v106, v107
	v_add_f32_e32 v107, v189, v168
	v_sub_f32_e32 v106, v107, v7
	v_med3_f32 v106, v106, s28, v236
	v_mul_f32_e32 v27, v27, v108
	v_sub_f32_e32 v107, v7, v107
	v_exp_f32_e32 v106, v106
	v_med3_f32 v107, v107, s28, v236
	v_add_f32_e32 v109, v188, v170
	s_nop 1
	v_exp_f32_e32 v107, v107
	global_store_dwordx2 v[92:93], v[150:151], off offset:1024
	v_cvt_pk_bf16_f32 v149, v118, v27
	v_mov_b32_e32 v108, v107
	v_sub_f32_e32 v107, v109, v103
	v_med3_f32 v107, v107, s28, v236
	v_sub_f32_e32 v109, v103, v109
	v_med3_f32 v109, v109, s28, v236
	v_exp_f32_e32 v107, v107
	global_store_dwordx2 v[114:115], v[148:149], off
	v_pk_mul_f32 v[106:107], v[36:37], v[106:107]
	v_exp_f32_e32 v109, v109
	v_cvt_pk_bf16_f32 v147, v106, v107
	v_add_f32_e32 v107, v187, v168
	v_sub_f32_e32 v106, v107, v7
	v_med3_f32 v106, v106, s28, v236
	v_pk_mul_f32 v[110:111], v[128:129], v[108:109]
	v_sub_f32_e32 v107, v7, v107
	v_exp_f32_e32 v106, v106
	v_med3_f32 v107, v107, s28, v236
	global_store_dwordx2 v[92:93], v[146:147], off offset:1280
	v_exp_f32_e32 v107, v107
	v_lshl_add_u64 v[114:115], v[60:61], 0, s[26:27]
	v_lshl_add_u64 v[72:73], v[114:115], 0, v[72:73]
	v_add_f32_e32 v108, v184, v170
	v_mul_f32_e32 v25, v25, v107
	v_sub_f32_e32 v107, v108, v103
	v_med3_f32 v107, v107, s28, v236
	v_sub_f32_e32 v108, v103, v108
	v_med3_f32 v108, v108, s28, v236
	v_exp_f32_e32 v107, v107
	v_cvt_pk_bf16_f32 v145, v110, v111
	v_pk_mul_f32 v[106:107], v[34:35], v[106:107]
	v_exp_f32_e32 v108, v108
	v_cvt_pk_bf16_f32 v143, v106, v107
	v_add_f32_e32 v107, v196, v168
	v_sub_f32_e32 v106, v107, v7
	v_med3_f32 v106, v106, s28, v236
	v_mul_f32_e32 v23, v23, v108
	v_sub_f32_e32 v107, v7, v107
	v_exp_f32_e32 v106, v106
	v_med3_f32 v107, v107, s28, v236
	v_add_f32_e32 v109, v200, v170
	s_nop 1
	v_exp_f32_e32 v107, v107
	global_store_dwordx2 v[92:93], v[142:143], off offset:1536
	v_cvt_pk_bf16_f32 v141, v25, v23
	v_mov_b32_e32 v108, v107
	v_sub_f32_e32 v107, v109, v103
	v_med3_f32 v107, v107, s28, v236
	v_sub_f32_e32 v109, v103, v109
	v_med3_f32 v109, v109, s28, v236
	v_exp_f32_e32 v107, v107
	global_store_dwordx2 v[126:127], v[144:145], off
	v_exp_f32_e32 v109, v109
	v_pk_mul_f32 v[106:107], v[32:33], v[106:107]
	global_store_dwordx2 v[122:123], v[140:141], off
	v_pk_mul_f32 v[112:113], v[116:117], v[108:109]
	v_cvt_pk_bf16_f32 v108, v138, v139
	v_cvt_pk_bf16_f32 v109, v106, v107
	global_store_dwordx2 v[92:93], v[108:109], off offset:1792
	v_lshlrev_b32_e32 v92, 1, v26
	v_mov_b32_e32 v93, v3
	v_cvt_pk_bf16_f32 v106, v136, v137
	v_cvt_pk_bf16_f32 v107, v112, v113
	v_lshl_add_u64 v[94:95], v[94:95], 0, v[92:93]
	global_store_dwordx2 v[94:95], v[106:107], off
	v_cvt_pk_bf16_f32 v106, v4, v130
	v_cvt_pk_bf16_f32 v107, v190, v132
	v_cvt_pk_bf16_f32 v108, v192, v134
	v_cvt_pk_bf16_f32 v109, v194, v136
	v_or_b32_e32 v4, 32, v19
	global_store_dwordx4 v[72:73], v[106:109], off
	v_lshlrev_b32_e32 v72, 1, v4
	v_mov_b32_e32 v73, v3
	v_cvt_pk_bf16_f32 v106, v124, v131
	v_cvt_pk_bf16_f32 v107, v191, v133
	v_cvt_pk_bf16_f32 v108, v193, v135
	v_cvt_pk_bf16_f32 v109, v195, v137
	v_lshl_add_u64 v[94:95], v[114:115], 0, v[72:73]
	v_or_b32_e32 v4, 64, v19
	global_store_dwordx4 v[94:95], v[106:109], off
	v_lshlrev_b32_e32 v94, 1, v4
	v_mov_b32_e32 v95, v3
	v_or_b32_e32 v4, 0x60, v19
	v_cvt_pk_bf16_f32 v106, v6, v96
	v_cvt_pk_bf16_f32 v107, v160, v104
	v_cvt_pk_bf16_f32 v108, v118, v110
	v_cvt_pk_bf16_f32 v109, v25, v112
	v_lshl_add_u64 v[116:117], v[114:115], 0, v[94:95]
	v_cvt_pk_bf16_f32 v104, v102, v97
	v_lshlrev_b32_e32 v96, 1, v4
	v_mov_b32_e32 v97, v3
	global_store_dwordx4 v[116:117], v[106:109], off
	s_nop 1
	v_cvt_pk_bf16_f32 v106, v27, v111
	v_cvt_pk_bf16_f32 v107, v23, v113
	v_lshl_add_u64 v[108:109], v[114:115], 0, v[96:97]
	global_store_dwordx4 v[108:109], v[104:107], off
	s_and_saveexec_b64 s[26:27], s[4:5]
	s_cbranch_execz .LBB0_177
	v_cndmask_b32_e64 v6, v202, v201, s[6:7]
	v_cndmask_b32_e64 v6, v6, v197, s[8:9]
	v_cndmask_b32_e64 v6, v6, v196, s[10:11]
	v_add_f32_e32 v23, v203, v7
	v_add_f32_e32 v23, v6, v23
	v_cndmask_b32_e64 v6, v182, v181, s[6:7]
	v_cndmask_b32_e64 v6, v6, v180, s[8:9]
	v_cndmask_b32_e64 v6, v6, v175, s[10:11]
	v_add_f32_e32 v25, v185, v125
	v_add_f32_e32 v6, v6, v25
	v_cndmask_b32_e64 v25, v177, v176, s[6:7]
	v_cndmask_b32_e64 v25, v25, v174, s[8:9]
	v_cndmask_b32_e64 v4, v206, v205, s[6:7]
	v_cndmask_b32_e64 v25, v25, v173, s[10:11]
	v_add_f32_e32 v27, v179, v5
	v_cmp_gt_f32_e32 vcc, s33, v5
	v_cndmask_b32_e64 v4, v4, v204, s[8:9]
	v_add_f32_e32 v25, v25, v27
	v_cndmask_b32_e32 v102, 0, v237, vcc
	v_cndmask_b32_e64 v4, v4, v200, s[10:11]
	v_add_f32_e32 v27, v207, v103
	v_add_f32_e32 v102, v5, v102
	v_sub_f32_e32 v5, v25, v5
	v_add_f32_e32 v27, v4, v27
	v_cndmask_b32_e32 v4, 0, v238, vcc
	v_cmp_gt_f32_e32 vcc, s33, v5
	v_sub_f32_e32 v6, v6, v125
	v_exp_f32_e32 v102, v102
	v_cndmask_b32_e32 v25, 0, v237, vcc
	v_add_f32_e32 v5, v5, v25
	v_exp_f32_e32 v5, v5
	v_cndmask_b32_e32 v25, 0, v238, vcc
	v_cmp_gt_f32_e32 vcc, s33, v125
	v_ldexp_f32 v4, v102, v4
	v_ldexp_f32 v104, v5, v25
	v_cndmask_b32_e32 v25, 0, v237, vcc
	v_add_f32_e32 v25, v125, v25
	v_exp_f32_e32 v25, v25
	v_cndmask_b32_e32 v5, 0, v238, vcc
	v_cmp_gt_f32_e32 vcc, s33, v6
	v_ldexp_f32 v5, v25, v5
	s_nop 0
	v_cndmask_b32_e32 v25, 0, v237, vcc
	v_add_f32_e32 v6, v6, v25
	v_exp_f32_e32 v6, v6
	v_cndmask_b32_e32 v25, 0, v238, vcc
	v_cmp_gt_f32_e32 vcc, s33, v7
	v_ldexp_f32 v105, v6, v25
	s_nop 0
	v_cndmask_b32_e32 v25, 0, v237, vcc
	v_add_f32_e32 v25, v7, v25
	v_sub_f32_e32 v7, v23, v7
	v_cndmask_b32_e32 v6, 0, v238, vcc
	v_cmp_gt_f32_e32 vcc, s33, v7
	v_exp_f32_e32 v25, v25
	s_nop 0
	v_cndmask_b32_e32 v23, 0, v237, vcc
	v_add_f32_e32 v7, v7, v23
	v_exp_f32_e32 v7, v7
	v_cndmask_b32_e32 v23, 0, v238, vcc
	v_cmp_gt_f32_e32 vcc, s33, v103
	v_ldexp_f32 v6, v25, v6
	v_ldexp_f32 v106, v7, v23
	v_cndmask_b32_e32 v23, 0, v237, vcc
	v_add_f32_e32 v23, v103, v23
	v_exp_f32_e32 v23, v23
	v_cndmask_b32_e32 v7, 0, v238, vcc
	v_ldexp_f32 v7, v23, v7
	global_store_dwordx4 v21, v[4:7], s[24:25]
	s_nop 1
	v_sub_f32_e32 v4, v27, v103
	v_cmp_gt_f32_e32 vcc, s33, v4
	s_nop 1
	v_cndmask_b32_e32 v5, 0, v237, vcc
	v_add_f32_e32 v4, v4, v5
	v_exp_f32_e32 v4, v4
	v_cndmask_b32_e32 v5, 0, v238, vcc
	v_ldexp_f32 v107, v4, v5
	global_store_dwordx4 v21, v[104:107], s[24:25] offset:512
.LBB0_177:
	s_or_b64 exec, exec, s[26:27]
	v_add_co_u32_e32 v4, vcc, 0x4000, v74
	global_load_dwordx2 v[62:63], v[62:63], off offset:1536
	s_nop 0
	v_addc_co_u32_e32 v5, vcc, 0, v75, vcc
	v_add_co_u32_e32 v68, vcc, 0x2000, v68
	global_load_dwordx2 v[66:67], v[66:67], off offset:512
	s_nop 0
	v_addc_co_u32_e32 v69, vcc, 0, v69, vcc
	global_load_dwordx2 v[68:69], v[68:69], off
	s_waitcnt vmcnt(0)
	v_lshlrev_b32_e32 v23, 16, v68
	global_load_dwordx2 v[64:65], v[64:65], off offset:1024
	v_mul_f32_e32 v23, 0xbfb8aa3b, v23
	v_exp_f32_e32 v23, v23
	v_and_b32_e32 v25, 0xffff0000, v68
	v_lshlrev_b32_e32 v27, 16, v69
	v_and_b32_e32 v68, 0xffff0000, v69
	v_add_f32_e32 v69, 1.0, v23
	v_rcp_f32_e32 v75, v69
	global_load_dwordx4 v[4:7], v[4:5], off
	v_fma_f32 v102, -v69, v75, 1.0
	v_fmac_f32_e32 v75, v102, v75
	v_div_fixup_f32 v106, v75, v69, 1.0
	v_mul_f32_e32 v105, v23, v106
	v_mul_f32_e32 v23, 0xbfb8aa3b, v25
	v_exp_f32_e32 v23, v23
	s_nop 0
	v_add_f32_e32 v25, 1.0, v23
	v_rcp_f32_e32 v74, v25
	s_nop 0
	v_fma_f32 v75, -v25, v74, 1.0
	v_fmac_f32_e32 v74, v75, v74
	v_div_fixup_f32 v108, v74, v25, 1.0
	v_mul_f32_e32 v107, v23, v108
	v_mul_f32_e32 v23, 0xbfb8aa3b, v27
	v_exp_f32_e32 v23, v23
	s_nop 0
	v_add_f32_e32 v25, 1.0, v23
	v_rcp_f32_e32 v69, v25
	s_nop 0
	v_fma_f32 v74, -v25, v69, 1.0
	v_fmac_f32_e32 v69, v74, v69
	v_div_fixup_f32 v27, v69, v25, 1.0
	v_mul_f32_e32 v25, 0xbfb8aa3b, v68
	v_exp_f32_e32 v25, v25
	v_mul_f32_e32 v23, v23, v27
	v_add_f32_e32 v68, 1.0, v25
	v_rcp_f32_e32 v74, v68
	s_nop 0
	v_fma_f32 v75, -v68, v74, 1.0
	v_fmac_f32_e32 v74, v75, v74
	v_div_fixup_f32 v104, v74, v68, 1.0
	v_lshlrev_b32_e32 v68, 16, v66
	v_and_b32_e32 v66, 0xffff0000, v66
	v_lshlrev_b32_e32 v74, 16, v67
	v_mul_f32_e32 v66, 0xbfb8aa3b, v66
	v_exp_f32_e32 v69, v66
	v_mul_f32_e32 v66, 0xbfb8aa3b, v74
	s_waitcnt vmcnt(1)
	v_lshlrev_b32_e32 v74, 16, v64
	v_mul_f32_e32 v74, 0xbfb8aa3b, v74
	v_exp_f32_e32 v74, v74
	v_and_b32_e32 v64, 0xffff0000, v64
	v_mul_f32_e32 v64, 0xbfb8aa3b, v64
	v_exp_f32_e32 v64, v64
	v_add_f32_e32 v102, 1.0, v74
	v_rcp_f32_e32 v109, v102
	v_lshlrev_b32_e32 v75, 16, v65
	v_and_b32_e32 v65, 0xffff0000, v65
	v_mul_f32_e32 v68, 0xbfb8aa3b, v68
	v_fma_f32 v110, -v102, v109, 1.0
	v_fmac_f32_e32 v109, v110, v109
	v_div_fixup_f32 v116, v109, v102, 1.0
	v_mul_f32_e32 v109, v74, v116
	v_add_f32_e32 v74, 1.0, v64
	v_rcp_f32_e32 v103, v74
	v_exp_f32_e32 v68, v68
	v_and_b32_e32 v67, 0xffff0000, v67
	v_mul_f32_e32 v67, 0xbfb8aa3b, v67
	v_fma_f32 v110, -v74, v103, 1.0
	v_fmac_f32_e32 v103, v110, v103
	v_div_fixup_f32 v115, v103, v74, 1.0
	v_mul_f32_e32 v114, v64, v115
	v_mul_f32_e32 v64, 0xbfb8aa3b, v75
	v_exp_f32_e32 v64, v64
	v_exp_f32_e32 v66, v66
	v_exp_f32_e32 v67, v67
	v_mul_f32_e32 v25, v25, v104
	v_add_f32_e32 v74, 1.0, v64
	v_rcp_f32_e32 v102, v74
	s_nop 0
	v_fma_f32 v103, -v74, v102, 1.0
	v_fmac_f32_e32 v102, v103, v102
	v_div_fixup_f32 v112, v102, v74, 1.0
	v_mul_f32_e32 v111, v64, v112
	v_mul_f32_e32 v64, 0xbfb8aa3b, v65
	v_exp_f32_e32 v64, v64
	s_nop 0
	v_add_f32_e32 v65, 1.0, v64
	v_rcp_f32_e32 v75, v65
	s_nop 0
	v_fma_f32 v102, -v65, v75, 1.0
	v_fmac_f32_e32 v75, v102, v75
	v_div_fixup_f32 v113, v75, v65, 1.0
	v_mul_f32_e32 v110, v64, v113
	v_lshlrev_b32_e32 v64, 16, v62
	v_and_b32_e32 v62, 0xffff0000, v62
	v_lshlrev_b32_e32 v74, 16, v63
	v_mul_f32_e32 v62, 0xbfb8aa3b, v62
	v_exp_f32_e32 v65, v62
	v_mul_f32_e32 v62, 0xbfb8aa3b, v74
	global_load_dwordx2 v[74:75], v[76:77], off offset:2048
	v_mul_f32_e32 v64, 0xbfb8aa3b, v64
	v_exp_f32_e32 v64, v64
	v_and_b32_e32 v63, 0xffff0000, v63
	v_mul_f32_e32 v63, 0xbfb8aa3b, v63
	v_exp_f32_e32 v62, v62
	v_exp_f32_e32 v63, v63
	s_waitcnt vmcnt(0)
	v_lshlrev_b32_e32 v76, 16, v74
	v_mul_f32_e32 v76, 0xbfb8aa3b, v76
	v_exp_f32_e32 v76, v76
	v_and_b32_e32 v74, 0xffff0000, v74
	v_mul_f32_e32 v74, 0xbfb8aa3b, v74
	v_exp_f32_e32 v74, v74
	v_add_f32_e32 v102, 1.0, v76
	v_rcp_f32_e32 v117, v102
	v_lshlrev_b32_e32 v77, 16, v75
	v_and_b32_e32 v75, 0xffff0000, v75
	v_fma_f32 v118, -v102, v117, 1.0
	v_fmac_f32_e32 v117, v118, v117
	v_div_fixup_f32 v130, v117, v102, 1.0
	v_mul_f32_e32 v121, v76, v130
	v_add_f32_e32 v76, 1.0, v74
	v_rcp_f32_e32 v103, v76
	s_nop 0
	v_fma_f32 v117, -v76, v103, 1.0
	v_fmac_f32_e32 v103, v117, v103
	v_div_fixup_f32 v129, v103, v76, 1.0
	v_mul_f32_e32 v128, v74, v129
	v_mul_f32_e32 v74, 0xbfb8aa3b, v77
	v_exp_f32_e32 v74, v74
	s_nop 0
	v_add_f32_e32 v76, 1.0, v74
	v_rcp_f32_e32 v102, v76
	s_nop 0
	v_fma_f32 v103, -v76, v102, 1.0
	v_fmac_f32_e32 v102, v103, v102
	v_div_fixup_f32 v119, v102, v76, 1.0
	v_mul_f32_e32 v118, v74, v119
	v_mul_f32_e32 v74, 0xbfb8aa3b, v75
	v_exp_f32_e32 v74, v74
	s_nop 0
	v_add_f32_e32 v75, 1.0, v74
	v_rcp_f32_e32 v77, v75
	s_nop 0
	v_fma_f32 v102, -v75, v77, 1.0
	v_fmac_f32_e32 v77, v102, v77
	v_div_fixup_f32 v120, v77, v75, 1.0
	v_mul_f32_e32 v117, v74, v120
	global_load_dwordx2 v[74:75], v[82:83], off offset:2560
	s_waitcnt vmcnt(0)
	v_lshlrev_b32_e32 v76, 16, v74
	v_and_b32_e32 v74, 0xffff0000, v74
	v_lshlrev_b32_e32 v77, 16, v75
	v_mul_f32_e32 v74, 0xbfb8aa3b, v74
	v_and_b32_e32 v75, 0xffff0000, v75
	v_exp_f32_e32 v103, v74
	v_mul_f32_e32 v74, 0xbfb8aa3b, v77
	v_exp_f32_e32 v82, v74
	v_mul_f32_e32 v74, 0xbfb8aa3b, v75
	v_exp_f32_e32 v83, v74
	global_load_dwordx2 v[74:75], v[80:81], off offset:3072
	v_mul_f32_e32 v76, 0xbfb8aa3b, v76
	v_exp_f32_e32 v102, v76
	s_waitcnt vmcnt(0)
	v_lshlrev_b32_e32 v76, 16, v74
	v_mul_f32_e32 v76, 0xbfb8aa3b, v76
	v_exp_f32_e32 v76, v76
	v_and_b32_e32 v74, 0xffff0000, v74
	v_mul_f32_e32 v74, 0xbfb8aa3b, v74
	v_exp_f32_e32 v74, v74
	v_add_f32_e32 v80, 1.0, v76
	v_rcp_f32_e32 v122, v80
	v_lshlrev_b32_e32 v77, 16, v75
	v_and_b32_e32 v75, 0xffff0000, v75
	v_fma_f32 v123, -v80, v122, 1.0
	v_fmac_f32_e32 v122, v123, v122
	v_div_fixup_f32 v137, v122, v80, 1.0
	v_mul_f32_e32 v131, v76, v137
	v_add_f32_e32 v76, 1.0, v74
	v_rcp_f32_e32 v81, v76
	s_nop 0
	v_fma_f32 v122, -v76, v81, 1.0
	v_fmac_f32_e32 v81, v122, v81
	v_div_fixup_f32 v135, v81, v76, 1.0
	v_mul_f32_e32 v133, v74, v135
	v_mul_f32_e32 v74, 0xbfb8aa3b, v77
	v_exp_f32_e32 v74, v74
	v_pk_add_f32 v[124:125], v[4:5], 1.0 op_sel_hi:[1,0] neg_lo:[1,0] neg_hi:[1,0]
	v_add_f32_e32 v76, 1.0, v74
	v_rcp_f32_e32 v80, v76
	v_mul_f32_e32 v140, v125, v107
	v_mul_f32_e32 v142, v124, v105
	v_mul_f32_e32 v160, v124, v109
	v_fma_f32 v81, -v76, v80, 1.0
	v_fmac_f32_e32 v80, v81, v80
	v_div_fixup_f32 v136, v80, v76, 1.0
	v_mul_f32_e32 v134, v74, v136
	v_mul_f32_e32 v74, 0xbfb8aa3b, v75
	v_exp_f32_e32 v74, v74
	v_mul_f32_e32 v148, v125, v133
	v_mul_f32_e32 v149, v124, v131
	v_mul_f32_e32 v162, v125, v114
	v_add_f32_e32 v75, 1.0, v74
	v_rcp_f32_e32 v77, v75
	s_mov_b64 s[26:27], 0x9000000
	v_mul_f32_e32 v159, v125, v128
	v_mul_f32_e32 v161, v124, v121
	v_fma_f32 v80, -v75, v77, 1.0
	v_fmac_f32_e32 v77, v80, v77
	v_div_fixup_f32 v138, v77, v75, 1.0
	v_mul_f32_e32 v132, v74, v138
	global_load_dwordx2 v[74:75], v[78:79], off offset:3584
	s_waitcnt vmcnt(0)
	v_lshlrev_b32_e32 v76, 16, v74
	v_and_b32_e32 v74, 0xffff0000, v74
	v_lshlrev_b32_e32 v77, 16, v75
	v_mul_f32_e32 v74, 0xbfb8aa3b, v74
	v_and_b32_e32 v75, 0xffff0000, v75
	v_exp_f32_e32 v127, v74
	v_mul_f32_e32 v74, 0xbfb8aa3b, v77
	v_exp_f32_e32 v80, v74
	v_mul_f32_e32 v74, 0xbfb8aa3b, v75
	v_exp_f32_e32 v81, v74
	v_lshl_add_u64 v[74:75], v[70:71], 0, s[26:27]
	s_mov_b64 s[26:27], 0xc000000
	v_mul_f32_e32 v76, 0xbfb8aa3b, v76
	v_lshl_add_u64 v[70:71], v[70:71], 0, s[26:27]
	v_exp_f32_e32 v126, v76
	v_lshl_add_u64 v[78:79], v[74:75], 0, v[2:3]
	v_lshl_add_u64 v[76:77], v[70:71], 0, v[2:3]
	v_fma_f32 v2, v124, v106, v4
	v_log_f32_e32 v2, v2
	v_pk_add_f32 v[106:107], v[68:69], 1.0 op_sel_hi:[1,0]
	v_max_f32_e32 v152, 0xc2c80000, v2
	v_fma_f32 v2, v125, v108, v5
	v_log_f32_e32 v2, v2
	s_nop 0
	v_max_f32_e32 v153, 0xc2c80000, v2
	v_rcp_f32_e32 v105, v107
	s_nop 0
	v_fma_f32 v108, -v107, v105, 1.0
	v_fmac_f32_e32 v105, v108, v105
	v_div_fixup_f32 v107, v105, v107, 1.0
	v_rcp_f32_e32 v105, v106
	s_nop 0
	v_fma_f32 v108, -v106, v105, 1.0
	v_fmac_f32_e32 v105, v108, v105
	v_div_fixup_f32 v106, v105, v106, 1.0
	v_pk_mul_f32 v[122:123], v[124:125], v[106:107]
	v_pk_add_f32 v[108:109], v[6:7], 1.0 op_sel_hi:[1,0] neg_lo:[1,0] neg_hi:[1,0]
	v_add_f32_e32 v2, v4, v122
	v_log_f32_e32 v2, v2
	v_pk_mul_f32 v[68:69], v[68:69], v[106:107]
	v_mul_f32_e32 v133, v109, v25
	v_lshl_add_u64 v[106:107], v[74:75], 0, v[84:85]
	v_max_f32_e32 v165, 0xc2c80000, v2
	v_add_f32_e32 v2, v5, v123
	v_log_f32_e32 v2, v2
	v_pk_mul_f32 v[122:123], v[124:125], v[68:69]
	v_pk_add_f32 v[68:69], v[66:67], 1.0 op_sel_hi:[1,0]
	v_mul_f32_e32 v131, v109, v110
	v_max_f32_e32 v166, 0xc2c80000, v2
	v_fma_f32 v2, v124, v116, v4
	v_log_f32_e32 v2, v2
	s_nop 0
	v_max_f32_e32 v169, 0xc2c80000, v2
	v_fma_f32 v2, v125, v115, v5
	v_log_f32_e32 v2, v2
	s_nop 0
	v_max_f32_e32 v170, 0xc2c80000, v2
	v_fma_f32 v2, v124, v130, v4
	v_log_f32_e32 v2, v2
	s_nop 0
	v_max_f32_e32 v130, 0xc2c80000, v2
	v_fma_f32 v2, v125, v129, v5
	v_log_f32_e32 v2, v2
	s_nop 0
	v_max_f32_e32 v171, 0xc2c80000, v2
	v_fma_f32 v2, v124, v137, v4
	v_log_f32_e32 v2, v2
	v_mul_f32_e32 v137, v108, v23
	v_max_f32_e32 v172, 0xc2c80000, v2
	v_fma_f32 v2, v125, v135, v5
	v_log_f32_e32 v2, v2
	v_mul_f32_e32 v135, v108, v111
	v_max_f32_e32 v173, 0xc2c80000, v2
	v_fma_f32 v2, v108, v27, v6
	v_log_f32_e32 v2, v2
	s_nop 0
	v_max_f32_e32 v139, 0xc2c80000, v2
	v_fma_f32 v2, v109, v104, v7
	v_log_f32_e32 v2, v2
	s_nop 0
	v_max_f32_e32 v141, 0xc2c80000, v2
	v_rcp_f32_e32 v23, v69
	s_nop 0
	v_fma_f32 v25, -v69, v23, 1.0
	v_fmac_f32_e32 v23, v25, v23
	v_div_fixup_f32 v69, v23, v69, 1.0
	v_rcp_f32_e32 v23, v68
	s_nop 0
	v_fma_f32 v25, -v68, v23, 1.0
	v_fmac_f32_e32 v23, v25, v23
	v_div_fixup_f32 v68, v23, v68, 1.0
	v_pk_mul_f32 v[104:105], v[108:109], v[68:69]
	v_pk_mul_f32 v[66:67], v[66:67], v[68:69]
	v_add_f32_e32 v2, v6, v104
	v_log_f32_e32 v2, v2
	v_lshl_add_u64 v[68:69], v[70:71], 0, v[86:87]
	v_mul_f32_e32 v23, v108, v134
	v_mul_f32_e32 v27, v108, v118
	v_max_f32_e32 v143, 0xc2c80000, v2
	v_add_f32_e32 v2, v7, v105
	v_log_f32_e32 v2, v2
	v_lshl_add_u64 v[104:105], v[70:71], 0, v[84:85]
	v_lshl_add_u64 v[84:85], v[74:75], 0, v[86:87]
	v_pk_add_f32 v[86:87], v[64:65], 1.0 op_sel_hi:[1,0]
	v_max_f32_e32 v150, 0xc2c80000, v2
	v_div_scale_f32 v110, s[26:27], v87, v87, 1.0
	v_fma_f32 v2, v108, v112, v6
	v_rcp_f32_e32 v111, v110
	v_log_f32_e32 v2, v2
	v_mul_f32_e32 v25, v109, v117
	v_pk_mul_f32 v[66:67], v[108:109], v[66:67]
	v_fma_f32 v112, -v110, v111, 1.0
	v_max_f32_e32 v151, 0xc2c80000, v2
	v_fma_f32 v2, v109, v113, v7
	v_fmac_f32_e32 v111, v112, v111
	v_div_scale_f32 v112, vcc, 1.0, v87, 1.0
	v_log_f32_e32 v2, v2
	v_mul_f32_e32 v113, v112, v111
	v_fma_f32 v114, -v110, v113, v112
	v_fmac_f32_e32 v113, v114, v111
	v_fma_f32 v110, -v110, v113, v112
	v_max_f32_e32 v154, 0xc2c80000, v2
	v_fma_f32 v2, v108, v119, v6
	v_div_fmas_f32 v110, v110, v111, v113
	v_log_f32_e32 v2, v2
	v_div_fixup_f32 v87, v110, v87, 1.0
	v_rcp_f32_e32 v111, v86
	v_max_f32_e32 v155, 0xc2c80000, v2
	v_fma_f32 v2, v109, v120, v7
	v_log_f32_e32 v2, v2
	v_fma_f32 v112, -v86, v111, 1.0
	v_fmac_f32_e32 v111, v112, v111
	v_max_f32_e32 v156, 0xc2c80000, v2
	v_fma_f32 v2, v108, v136, v6
	v_log_f32_e32 v2, v2
	v_div_fixup_f32 v86, v111, v86, 1.0
	v_pk_mul_f32 v[64:65], v[64:65], v[86:87]
	v_pk_mul_f32 v[86:87], v[124:125], v[86:87]
	v_max_f32_e32 v157, 0xc2c80000, v2
	v_fma_f32 v2, v109, v138, v7
	v_add_f32_e32 v86, v4, v86
	v_log_f32_e32 v2, v2
	v_log_f32_e32 v86, v86
	v_pk_mul_f32 v[128:129], v[124:125], v[64:65]
	v_pk_add_f32 v[64:65], v[62:63], 1.0 op_sel_hi:[1,0]
	v_max_f32_e32 v158, 0xc2c80000, v2
	v_mul_f32_e32 v2, v109, v132
	v_max_f32_e32 v132, 0xc2c80000, v86
	v_add_f32_e32 v86, v5, v87
	v_log_f32_e32 v86, v86
	v_lshl_add_u64 v[118:119], v[74:75], 0, v[98:99]
	v_max_f32_e32 v134, 0xc2c80000, v86
	v_rcp_f32_e32 v87, v65
	s_nop 0
	v_fma_f32 v110, -v65, v87, 1.0
	v_fmac_f32_e32 v87, v110, v87
	v_div_fixup_f32 v65, v87, v65, 1.0
	v_rcp_f32_e32 v87, v64
	s_nop 0
	v_fma_f32 v110, -v64, v87, 1.0
	v_fmac_f32_e32 v87, v110, v87
	v_div_fixup_f32 v64, v87, v64, 1.0
	v_pk_mul_f32 v[62:63], v[62:63], v[64:65]
	v_pk_mul_f32 v[64:65], v[108:109], v[64:65]
	v_pk_add_f32 v[86:87], v[102:103], 1.0 op_sel_hi:[1,0]
	v_add_f32_e32 v64, v6, v64
	v_log_f32_e32 v64, v64
	v_lshl_add_u64 v[112:113], v[74:75], 0, v[88:89]
	v_lshl_add_u64 v[110:111], v[70:71], 0, v[88:89]
	v_div_scale_f32 v88, s[26:27], v87, v87, 1.0
	v_max_f32_e32 v163, 0xc2c80000, v64
	v_add_f32_e32 v64, v7, v65
	v_log_f32_e32 v64, v64
	v_rcp_f32_e32 v89, v88
	v_pk_mul_f32 v[114:115], v[108:109], v[62:63]
	v_lshl_add_u64 v[62:63], v[70:71], 0, v[90:91]
	v_max_f32_e32 v164, 0xc2c80000, v64
	v_lshl_add_u64 v[64:65], v[74:75], 0, v[90:91]
	v_fma_f32 v90, -v88, v89, 1.0
	v_fmac_f32_e32 v89, v90, v89
	v_div_scale_f32 v90, vcc, 1.0, v87, 1.0
	v_mul_f32_e32 v91, v90, v89
	v_fma_f32 v116, -v88, v91, v90
	v_fmac_f32_e32 v91, v116, v89
	v_fma_f32 v88, -v88, v91, v90
	v_div_fmas_f32 v88, v88, v89, v91
	v_div_fixup_f32 v87, v88, v87, 1.0
	v_rcp_f32_e32 v89, v86
	s_nop 0
	v_fma_f32 v90, -v86, v89, 1.0
	v_fmac_f32_e32 v89, v90, v89
	v_div_fixup_f32 v86, v89, v86, 1.0
	v_pk_mul_f32 v[88:89], v[102:103], v[86:87]
	v_pk_mul_f32 v[86:87], v[124:125], v[86:87]
	v_pk_mul_f32 v[144:145], v[124:125], v[88:89]
	v_add_f32_e32 v86, v4, v86
	v_log_f32_e32 v86, v86
	s_nop 0
	v_max_f32_e32 v102, 0xc2c80000, v86
	v_add_f32_e32 v86, v5, v87
	v_log_f32_e32 v86, v86
	s_nop 0
	v_max_f32_e32 v103, 0xc2c80000, v86
	v_pk_add_f32 v[86:87], v[82:83], 1.0 op_sel_hi:[1,0]
	s_nop 0
	v_rcp_f32_e32 v89, v87
	s_nop 0
	v_fma_f32 v90, -v87, v89, 1.0
	v_fmac_f32_e32 v89, v90, v89
	v_div_fixup_f32 v87, v89, v87, 1.0
	v_rcp_f32_e32 v89, v86
	s_nop 0
	v_fma_f32 v90, -v86, v89, 1.0
	v_fmac_f32_e32 v89, v90, v89
	v_div_fixup_f32 v86, v89, v86, 1.0
	v_pk_mul_f32 v[82:83], v[82:83], v[86:87]
	v_pk_mul_f32 v[86:87], v[108:109], v[86:87]
	v_pk_mul_f32 v[120:121], v[108:109], v[82:83]
	v_add_f32_e32 v86, v6, v86
	v_log_f32_e32 v86, v86
	v_pk_add_f32 v[82:83], v[126:127], 1.0 op_sel_hi:[1,0]
	v_lshl_add_u64 v[116:117], v[70:71], 0, v[98:99]
	v_div_scale_f32 v90, s[26:27], v83, v83, 1.0
	v_rcp_f32_e32 v91, v90
	v_max_f32_e32 v167, 0xc2c80000, v86
	v_add_f32_e32 v86, v7, v87
	v_log_f32_e32 v86, v86
	v_fma_f32 v98, -v90, v91, 1.0
	v_fmac_f32_e32 v91, v98, v91
	v_div_scale_f32 v98, vcc, 1.0, v83, 1.0
	v_mul_f32_e32 v99, v98, v91
	v_max_f32_e32 v168, 0xc2c80000, v86
	v_lshl_add_u64 v[88:89], v[74:75], 0, v[100:101]
	v_lshl_add_u64 v[86:87], v[70:71], 0, v[100:101]
	v_fma_f32 v100, -v90, v99, v98
	v_fmac_f32_e32 v99, v100, v91
	v_fma_f32 v90, -v90, v99, v98
	v_div_fmas_f32 v90, v90, v91, v99
	v_div_fixup_f32 v83, v90, v83, 1.0
	v_rcp_f32_e32 v91, v82
	s_nop 0
	v_fma_f32 v98, -v82, v91, 1.0
	v_fmac_f32_e32 v91, v98, v91
	v_div_fixup_f32 v82, v91, v82, 1.0
	v_pk_mul_f32 v[90:91], v[126:127], v[82:83]
	v_pk_mul_f32 v[82:83], v[124:125], v[82:83]
	v_pk_mul_f32 v[146:147], v[124:125], v[90:91]
	v_add_f32_e32 v4, v4, v82
	v_log_f32_e32 v4, v4
	s_nop 0
	v_max_f32_e32 v174, 0xc2c80000, v4
	v_add_f32_e32 v4, v5, v83
	v_log_f32_e32 v4, v4
	v_add_f32_e32 v172, v172, v174
	v_add_f32_e32 v175, v102, v172
	v_add_f32_e32 v124, v130, v175
	v_add_f32_e32 v130, v132, v124
	v_max_f32_e32 v127, 0xc2c80000, v4
	v_add_f32_e32 v132, v169, v130
	v_add_f32_e32 v125, v173, v127
	v_add_f32_e32 v136, v165, v132
	v_add_f32_e32 v173, v103, v125
	v_add_f32_e32 v4, v152, v136
	v_add_f32_e32 v126, v171, v173
	ds_bpermute_b32 v90, v13, v4
	ds_bpermute_b32 v98, v15, v4
	v_add_f32_e32 v176, v134, v126
	ds_bpermute_b32 v83, v9, v4
	v_add_f32_e32 v134, v170, v176
	v_add_f32_e32 v138, v166, v134
	v_add_f32_e32 v82, v153, v138
	s_waitcnt lgkmcnt(1)
	v_cndmask_b32_e64 v5, v98, v90, s[4:5]
	v_cndmask_b32_e64 v91, v98, v90, s[6:7]
	ds_bpermute_b32 v99, v13, v82
	ds_bpermute_b32 v100, v15, v82
	s_waitcnt lgkmcnt(2)
	v_cndmask_b32_e64 v5, v5, v83, s[10:11]
	v_cndmask_b32_e64 v91, v91, v83, s[8:9]
	v_cndmask_b32_e64 v90, v98, v90, s[10:11]
	ds_bpermute_b32 v98, v9, v82
	v_cndmask_b32_e64 v5, v5, v4, s[8:9]
	v_cndmask_b32_e64 v91, v91, v4, s[10:11]
	v_cndmask_b32_e64 v83, v90, v83, s[4:5]
	v_cndmask_b32_e64 v152, v83, v4, s[6:7]
	v_cndmask_b32_e64 v83, 0, v91, s[12:13]
	v_cndmask_b32_e64 v90, 0, v5, s[14:15]
	v_add_f32_e32 v83, v83, v90
	v_cndmask_b32_e64 v90, 0, v152, s[4:5]
	v_add_f32_e32 v90, v90, v83
	s_waitcnt lgkmcnt(1)
	v_cndmask_b32_e64 v83, v100, v99, s[4:5]
	v_cndmask_b32_e64 v101, v100, v99, s[6:7]
	s_waitcnt lgkmcnt(0)
	v_cndmask_b32_e64 v83, v83, v98, s[10:11]
	v_cndmask_b32_e64 v101, v101, v98, s[8:9]
	v_cndmask_b32_e64 v99, v100, v99, s[10:11]
	v_cndmask_b32_e64 v83, v83, v82, s[8:9]
	v_cndmask_b32_e64 v101, v101, v82, s[10:11]
	v_cndmask_b32_e64 v98, v99, v98, s[4:5]
	v_cndmask_b32_e64 v153, v98, v82, s[6:7]
	v_cndmask_b32_e64 v98, 0, v101, s[12:13]
	v_cndmask_b32_e64 v99, 0, v83, s[14:15]
	v_add_f32_e32 v98, v98, v99
	v_cndmask_b32_e64 v99, 0, v153, s[4:5]
	v_add_f32_e32 v100, v99, v98
	v_pk_add_f32 v[98:99], v[4:5], v[90:91]
	s_nop 0
	v_sub_f32_e32 v102, v98, v99
	v_med3_f32 v102, v102, s28, v236
	v_sub_f32_e32 v98, v99, v98
	v_med3_f32 v98, v98, s28, v236
	v_exp_f32_e32 v102, v102
	s_nop 0
	v_mov_b32_e32 v170, v102
	s_nop 0
	v_exp_f32_e32 v98, v98
	v_pk_add_f32 v[102:103], v[82:83], v[100:101]
	v_mul_f32_e32 v98, v142, v98
	v_sub_f32_e32 v142, v102, v103
	v_med3_f32 v142, v142, s28, v236
	v_sub_f32_e32 v102, v103, v102
	v_med3_f32 v102, v102, s28, v236
	v_exp_f32_e32 v142, v142
	s_nop 0
	v_mov_b32_e32 v171, v142
	s_nop 0
	v_exp_f32_e32 v102, v102
	v_pk_mul_f32 v[46:47], v[46:47], v[170:171]
	v_cvt_pk_bf16_f32 v142, v46, v47
	v_add_f32_e32 v47, v136, v90
	v_sub_f32_e32 v46, v47, v99
	v_med3_f32 v46, v46, s28, v236
	v_sub_f32_e32 v47, v99, v47
	v_med3_f32 v47, v47, s28, v236
	v_exp_f32_e32 v46, v46
	v_mul_f32_e32 v102, v140, v102
	s_nop 1
	v_exp_f32_e32 v47, v47
	v_cvt_pk_bf16_f32 v140, v98, v102
	v_mov_b32_e32 v170, v47
	v_add_f32_e32 v136, v138, v100
	v_sub_f32_e32 v47, v136, v103
	v_med3_f32 v47, v47, s28, v236
	s_nop 1
	v_exp_f32_e32 v47, v47
	s_nop 0
	v_pk_mul_f32 v[46:47], v[44:45], v[46:47]
	v_sub_f32_e32 v44, v103, v136
	v_med3_f32 v44, v44, s28, v236
	v_cvt_pk_bf16_f32 v138, v46, v47
	v_add_f32_e32 v47, v132, v90
	v_exp_f32_e32 v44, v44
	v_sub_f32_e32 v46, v47, v99
	v_med3_f32 v46, v46, s28, v236
	v_mov_b32_e32 v171, v44
	v_pk_mul_f32 v[44:45], v[122:123], v[170:171]
	v_sub_f32_e32 v47, v99, v47
	v_exp_f32_e32 v46, v46
	v_med3_f32 v47, v47, s28, v236
	v_cvt_pk_bf16_f32 v136, v44, v45
	v_exp_f32_e32 v47, v47
	v_add_f32_e32 v122, v134, v100
	v_mul_f32_e32 v160, v160, v47
	v_sub_f32_e32 v47, v122, v103
	v_med3_f32 v47, v47, s28, v236
	s_nop 1
	v_exp_f32_e32 v47, v47
	s_nop 0
	v_pk_mul_f32 v[46:47], v[58:59], v[46:47]
	v_sub_f32_e32 v58, v103, v122
	v_med3_f32 v58, v58, s28, v236
	v_cvt_pk_bf16_f32 v134, v46, v47
	v_add_f32_e32 v47, v130, v90
	v_exp_f32_e32 v58, v58
	v_sub_f32_e32 v46, v47, v99
	v_med3_f32 v46, v46, s28, v236
	v_mul_f32_e32 v162, v162, v58
	v_sub_f32_e32 v47, v99, v47
	v_exp_f32_e32 v46, v46
	v_med3_f32 v47, v47, s28, v236
	v_add_f32_e32 v59, v176, v100
	s_nop 1
	v_exp_f32_e32 v47, v47
	v_cvt_pk_bf16_f32 v132, v160, v162
	v_mov_b32_e32 v58, v47
	v_sub_f32_e32 v47, v59, v103
	v_med3_f32 v47, v47, s28, v236
	s_nop 1
	v_exp_f32_e32 v47, v47
	s_nop 0
	v_pk_mul_f32 v[56:57], v[56:57], v[46:47]
	v_sub_f32_e32 v46, v103, v59
	v_med3_f32 v46, v46, s28, v236
	v_cvt_pk_bf16_f32 v130, v56, v57
	v_add_f32_e32 v57, v124, v90
	v_exp_f32_e32 v46, v46
	v_sub_f32_e32 v56, v57, v99
	v_med3_f32 v56, v56, s28, v236
	v_mov_b32_e32 v59, v46
	v_pk_mul_f32 v[46:47], v[128:129], v[58:59]
	v_sub_f32_e32 v57, v99, v57
	v_exp_f32_e32 v56, v56
	v_med3_f32 v57, v57, s28, v236
	v_cvt_pk_bf16_f32 v128, v46, v47
	v_exp_f32_e32 v57, v57
	v_add_f32_e32 v58, v126, v100
	v_mul_f32_e32 v161, v161, v57
	v_sub_f32_e32 v57, v58, v103
	v_med3_f32 v57, v57, s28, v236
	s_nop 1
	v_exp_f32_e32 v57, v57
	s_nop 0
	v_pk_mul_f32 v[54:55], v[54:55], v[56:57]
	v_sub_f32_e32 v56, v103, v58
	v_med3_f32 v56, v56, s28, v236
	v_cvt_pk_bf16_f32 v126, v54, v55
	v_add_f32_e32 v55, v175, v90
	v_exp_f32_e32 v56, v56
	v_sub_f32_e32 v54, v55, v99
	v_med3_f32 v54, v54, s28, v236
	v_mul_f32_e32 v159, v159, v56
	v_sub_f32_e32 v55, v99, v55
	v_exp_f32_e32 v54, v54
	v_med3_f32 v55, v55, s28, v236
	v_add_f32_e32 v57, v173, v100
	s_nop 1
	v_exp_f32_e32 v55, v55
	v_cvt_pk_bf16_f32 v124, v161, v159
	v_mov_b32_e32 v56, v55
	v_sub_f32_e32 v55, v57, v103
	v_med3_f32 v55, v55, s28, v236
	s_nop 1
	v_exp_f32_e32 v55, v55
	s_nop 0
	v_pk_mul_f32 v[54:55], v[52:53], v[54:55]
	v_sub_f32_e32 v52, v103, v57
	v_med3_f32 v52, v52, s28, v236
	v_cvt_pk_bf16_f32 v122, v54, v55
	v_add_f32_e32 v55, v172, v90
	v_exp_f32_e32 v52, v52
	v_sub_f32_e32 v54, v55, v99
	v_med3_f32 v54, v54, s28, v236
	v_mov_b32_e32 v57, v52
	v_pk_mul_f32 v[52:53], v[144:145], v[56:57]
	v_sub_f32_e32 v55, v99, v55
	v_exp_f32_e32 v54, v54
	v_med3_f32 v55, v55, s28, v236
	v_cvt_pk_bf16_f32 v58, v52, v53
	v_exp_f32_e32 v55, v55
	v_add_f32_e32 v56, v125, v100
	v_mul_f32_e32 v165, v149, v55
	v_sub_f32_e32 v55, v56, v103
	v_med3_f32 v55, v55, s28, v236
	s_nop 1
	v_exp_f32_e32 v55, v55
	s_nop 0
	v_pk_mul_f32 v[50:51], v[50:51], v[54:55]
	v_sub_f32_e32 v54, v103, v56
	v_med3_f32 v54, v54, s28, v236
	v_cvt_pk_bf16_f32 v56, v50, v51
	v_add_f32_e32 v51, v174, v90
	v_exp_f32_e32 v54, v54
	v_sub_f32_e32 v50, v51, v99
	v_med3_f32 v50, v50, s28, v236
	v_sub_f32_e32 v51, v99, v51
	v_exp_f32_e32 v50, v50
	v_med3_f32 v51, v51, s28, v236
	v_mul_f32_e32 v166, v148, v54
	s_nop 1
	v_exp_f32_e32 v51, v51
	v_cvt_pk_bf16_f32 v54, v165, v166
	v_mov_b32_e32 v144, v51
	v_add_f32_e32 v55, v127, v100
	v_sub_f32_e32 v51, v55, v103
	v_med3_f32 v51, v51, s28, v236
	s_nop 1
	v_exp_f32_e32 v51, v51
	s_nop 0
	v_pk_mul_f32 v[50:51], v[48:49], v[50:51]
	v_sub_f32_e32 v48, v103, v55
	v_med3_f32 v48, v48, s28, v236
	s_nop 1
	v_exp_f32_e32 v48, v48
	s_nop 0
	v_mov_b32_e32 v145, v48
	v_pk_mul_f32 v[48:49], v[146:147], v[144:145]
	v_pk_add_f32 v[144:145], v[80:81], 1.0 op_sel_hi:[1,0]
	s_nop 0
	v_rcp_f32_e32 v57, v145
	s_nop 0
	v_fma_f32 v59, -v145, v57, 1.0
	v_fmac_f32_e32 v57, v59, v57
	v_div_fixup_f32 v145, v57, v145, 1.0
	v_rcp_f32_e32 v57, v144
	s_mov_b64 s[26:27], 0xf000000
	v_fma_f32 v59, -v144, v57, 1.0
	v_fmac_f32_e32 v57, v59, v57
	v_div_fixup_f32 v144, v57, v144, 1.0
	v_pk_mul_f32 v[80:81], v[80:81], v[144:145]
	v_pk_mul_f32 v[144:145], v[108:109], v[144:145]
	v_pk_mul_f32 v[148:149], v[108:109], v[80:81]
	v_add_f32_e32 v6, v6, v144
	v_log_f32_e32 v6, v6
	s_nop 0
	v_max_f32_e32 v170, 0xc2c80000, v6
	v_add_f32_e32 v57, v157, v170
	v_add_f32_e32 v123, v167, v57
	v_add_f32_e32 v125, v155, v123
	v_add_f32_e32 v6, v7, v145
	v_add_f32_e32 v129, v163, v125
	v_log_f32_e32 v6, v6
	v_add_f32_e32 v157, v151, v129
	v_add_f32_e32 v163, v143, v157
	v_add_f32_e32 v80, v139, v163
	ds_bpermute_b32 v90, v13, v80
	ds_bpermute_b32 v100, v15, v80
	v_max_f32_e32 v169, 0xc2c80000, v6
	ds_bpermute_b32 v7, v9, v80
	v_add_f32_e32 v55, v158, v169
	v_add_f32_e32 v59, v168, v55
	v_add_f32_e32 v127, v156, v59
	v_add_f32_e32 v156, v164, v127
	s_waitcnt lgkmcnt(1)
	v_cndmask_b32_e64 v81, v100, v90, s[4:5]
	v_cndmask_b32_e64 v108, v100, v90, s[6:7]
	v_add_f32_e32 v158, v154, v156
	s_waitcnt lgkmcnt(0)
	v_cndmask_b32_e64 v81, v81, v7, s[10:11]
	v_cndmask_b32_e64 v108, v108, v7, s[8:9]
	v_cndmask_b32_e64 v90, v100, v90, s[10:11]
	v_add_f32_e32 v164, v150, v158
	v_cndmask_b32_e64 v81, v81, v80, s[8:9]
	v_cndmask_b32_e64 v147, v108, v80, s[10:11]
	v_cndmask_b32_e64 v7, v90, v7, s[4:5]
	v_add_f32_e32 v6, v141, v164
	v_cndmask_b32_e64 v90, v7, v80, s[6:7]
	v_cndmask_b32_e64 v7, 0, v147, s[12:13]
	v_cndmask_b32_e64 v100, 0, v81, s[14:15]
	v_add_f32_e32 v7, v7, v100
	v_cndmask_b32_e64 v100, 0, v90, s[4:5]
	ds_bpermute_b32 v108, v13, v6
	ds_bpermute_b32 v109, v15, v6
	v_add_f32_e32 v146, v100, v7
	ds_bpermute_b32 v100, v9, v6
	s_waitcnt lgkmcnt(1)
	v_cndmask_b32_e64 v7, v109, v108, s[4:5]
	v_cndmask_b32_e64 v139, v109, v108, s[6:7]
	s_waitcnt lgkmcnt(0)
	v_cndmask_b32_e64 v7, v7, v100, s[10:11]
	v_cndmask_b32_e64 v139, v139, v100, s[8:9]
	v_cndmask_b32_e64 v108, v109, v108, s[10:11]
	v_cndmask_b32_e64 v7, v7, v6, s[8:9]
	v_cndmask_b32_e64 v151, v139, v6, s[10:11]
	v_cndmask_b32_e64 v100, v108, v100, s[4:5]
	v_cndmask_b32_e64 v100, v100, v6, s[6:7]
	v_cndmask_b32_e64 v109, 0, v151, s[12:13]
	v_cndmask_b32_e64 v139, 0, v7, s[14:15]
	v_cndmask_b32_e64 v108, 0, v100, s[4:5]
	v_add_f32_e32 v109, v109, v139
	v_add_f32_e32 v150, v108, v109
	v_pk_add_f32 v[108:109], v[80:81], v[146:147]
	v_pk_add_f32 v[144:145], v[6:7], v[150:151]
	v_sub_f32_e32 v139, v108, v109
	v_med3_f32 v139, v139, s28, v236
	v_sub_f32_e32 v108, v109, v108
	v_med3_f32 v108, v108, s28, v236
	v_exp_f32_e32 v139, v139
	s_nop 0
	v_mov_b32_e32 v154, v139
	s_nop 0
	v_exp_f32_e32 v108, v108
	s_nop 0
	v_mul_f32_e32 v108, v137, v108
	v_sub_f32_e32 v137, v144, v145
	v_med3_f32 v137, v137, s28, v236
	s_nop 1
	v_exp_f32_e32 v137, v137
	s_nop 0
	v_mov_b32_e32 v155, v137
	v_sub_f32_e32 v137, v145, v144
	v_med3_f32 v137, v137, s28, v236
	v_pk_mul_f32 v[30:31], v[30:31], v[154:155]
	s_nop 0
	v_exp_f32_e32 v137, v137
	v_cvt_pk_bf16_f32 v143, v30, v31
	v_add_f32_e32 v31, v163, v146
	v_sub_f32_e32 v30, v31, v109
	v_mul_f32_e32 v144, v133, v137
	v_med3_f32 v30, v30, s28, v236
	v_cvt_pk_bf16_f32 v141, v108, v144
	global_store_dwordx2 v[76:77], v[140:141], off
	v_sub_f32_e32 v31, v109, v31
	v_exp_f32_e32 v30, v30
	v_med3_f32 v31, v31, s28, v236
	v_add_f32_e32 v77, v164, v150
	s_nop 1
	v_exp_f32_e32 v31, v31
	global_store_dwordx2 v[78:79], v[142:143], off
	v_mov_b32_e32 v76, v31
	v_sub_f32_e32 v31, v77, v145
	v_med3_f32 v31, v31, s28, v236
	s_nop 1
	v_exp_f32_e32 v31, v31
	s_nop 0
	v_pk_mul_f32 v[30:31], v[28:29], v[30:31]
	v_sub_f32_e32 v28, v145, v77
	v_med3_f32 v28, v28, s28, v236
	v_cvt_pk_bf16_f32 v139, v30, v31
	v_add_f32_e32 v31, v157, v146
	v_exp_f32_e32 v28, v28
	v_sub_f32_e32 v30, v31, v109
	v_med3_f32 v30, v30, s28, v236
	v_mov_b32_e32 v77, v28
	v_pk_mul_f32 v[28:29], v[66:67], v[76:77]
	v_sub_f32_e32 v31, v109, v31
	v_exp_f32_e32 v30, v30
	v_med3_f32 v31, v31, s28, v236
	v_add_f32_e32 v67, v158, v150
	v_exp_f32_e32 v31, v31
	v_cvt_pk_bf16_f32 v137, v28, v29
	global_store_dwordx2 v[106:107], v[138:139], off
	v_mul_f32_e32 v66, v135, v31
	v_sub_f32_e32 v31, v67, v145
	v_med3_f32 v31, v31, s28, v236
	global_store_dwordx2 v[104:105], v[136:137], off
	s_nop 0
	v_exp_f32_e32 v31, v31
	s_nop 0
	v_pk_mul_f32 v[30:31], v[42:43], v[30:31]
	v_sub_f32_e32 v42, v145, v67
	v_med3_f32 v42, v42, s28, v236
	v_cvt_pk_bf16_f32 v135, v30, v31
	v_add_f32_e32 v31, v129, v146
	v_exp_f32_e32 v42, v42
	v_sub_f32_e32 v30, v31, v109
	v_med3_f32 v30, v30, s28, v236
	v_mul_f32_e32 v67, v131, v42
	v_sub_f32_e32 v31, v109, v31
	v_exp_f32_e32 v30, v30
	v_med3_f32 v31, v31, s28, v236
	v_add_f32_e32 v43, v156, v150
	s_nop 1
	v_exp_f32_e32 v31, v31
	v_cvt_pk_bf16_f32 v133, v66, v67
	global_store_dwordx2 v[68:69], v[132:133], off
	v_mov_b32_e32 v42, v31
	v_sub_f32_e32 v31, v43, v145
	v_med3_f32 v31, v31, s28, v236
	global_store_dwordx2 v[84:85], v[134:135], off
	s_nop 0
	v_exp_f32_e32 v31, v31
	s_nop 0
	v_pk_mul_f32 v[40:41], v[40:41], v[30:31]
	v_sub_f32_e32 v30, v145, v43
	v_med3_f32 v30, v30, s28, v236
	v_cvt_pk_bf16_f32 v131, v40, v41
	v_add_f32_e32 v41, v125, v146
	v_exp_f32_e32 v30, v30
	v_sub_f32_e32 v40, v41, v109
	v_med3_f32 v40, v40, s28, v236
	v_mov_b32_e32 v43, v30
	v_pk_mul_f32 v[30:31], v[114:115], v[42:43]
	v_sub_f32_e32 v41, v109, v41
	v_exp_f32_e32 v40, v40
	v_med3_f32 v41, v41, s28, v236
	v_cvt_pk_bf16_f32 v129, v30, v31
	v_exp_f32_e32 v41, v41
	global_store_dwordx2 v[112:113], v[130:131], off
	global_store_dwordx2 v[110:111], v[128:129], off
	v_add_f32_e32 v42, v127, v150
	v_mul_f32_e32 v27, v27, v41
	v_sub_f32_e32 v41, v42, v145
	v_med3_f32 v41, v41, s28, v236
	s_nop 1
	v_exp_f32_e32 v41, v41
	s_nop 0
	v_pk_mul_f32 v[38:39], v[38:39], v[40:41]
	v_sub_f32_e32 v40, v145, v42
	v_med3_f32 v40, v40, s28, v236
	v_cvt_pk_bf16_f32 v127, v38, v39
	v_add_f32_e32 v39, v123, v146
	v_exp_f32_e32 v40, v40
	v_sub_f32_e32 v38, v39, v109
	v_med3_f32 v38, v38, s28, v236
	v_mul_f32_e32 v25, v25, v40
	v_sub_f32_e32 v39, v109, v39
	v_exp_f32_e32 v38, v38
	v_med3_f32 v39, v39, s28, v236
	v_add_f32_e32 v41, v59, v150
	s_nop 1
	v_exp_f32_e32 v39, v39
	v_cvt_pk_bf16_f32 v125, v27, v25
	global_store_dwordx2 v[64:65], v[126:127], off
	v_mov_b32_e32 v40, v39
	v_sub_f32_e32 v39, v41, v145
	v_med3_f32 v39, v39, s28, v236
	global_store_dwordx2 v[62:63], v[124:125], off
	s_nop 0
	v_exp_f32_e32 v39, v39
	s_nop 0
	v_pk_mul_f32 v[36:37], v[36:37], v[38:39]
	v_sub_f32_e32 v38, v145, v41
	v_med3_f32 v38, v38, s28, v236
	v_cvt_pk_bf16_f32 v123, v36, v37
	v_add_f32_e32 v37, v57, v146
	v_exp_f32_e32 v38, v38
	v_sub_f32_e32 v36, v37, v109
	v_med3_f32 v36, v36, s28, v236
	v_mov_b32_e32 v41, v38
	v_pk_mul_f32 v[38:39], v[120:121], v[40:41]
	v_sub_f32_e32 v37, v109, v37
	v_exp_f32_e32 v36, v36
	v_med3_f32 v37, v37, s28, v236
	v_cvt_pk_bf16_f32 v59, v38, v39
	v_exp_f32_e32 v37, v37
	global_store_dwordx2 v[116:117], v[58:59], off
	global_store_dwordx2 v[118:119], v[122:123], off
	v_add_f32_e32 v40, v55, v150
	v_mul_f32_e32 v23, v23, v37
	v_sub_f32_e32 v37, v40, v145
	v_med3_f32 v37, v37, s28, v236
	s_nop 1
	v_exp_f32_e32 v37, v37
	s_nop 0
	v_pk_mul_f32 v[34:35], v[34:35], v[36:37]
	v_sub_f32_e32 v36, v145, v40
	v_med3_f32 v36, v36, s28, v236
	v_cvt_pk_bf16_f32 v57, v34, v35
	v_lshl_add_u64 v[40:41], v[60:61], 0, s[26:27]
	v_exp_f32_e32 v36, v36
	global_store_dwordx2 v[88:89], v[56:57], off
	v_mul_f32_e32 v58, v2, v36
	v_add_f32_e32 v2, v170, v146
	v_sub_f32_e32 v34, v2, v109
	v_med3_f32 v34, v34, s28, v236
	v_sub_f32_e32 v2, v109, v2
	v_med3_f32 v2, v2, s28, v236
	v_exp_f32_e32 v34, v34
	v_cvt_pk_bf16_f32 v55, v23, v58
	s_nop 1
	v_exp_f32_e32 v2, v2
	global_store_dwordx2 v[86:87], v[54:55], off
	v_mov_b32_e32 v36, v2
	v_add_f32_e32 v2, v169, v150
	v_sub_f32_e32 v35, v2, v145
	v_med3_f32 v35, v35, s28, v236
	v_sub_f32_e32 v2, v145, v2
	v_med3_f32 v2, v2, s28, v236
	v_exp_f32_e32 v35, v35
	s_nop 0
	v_pk_mul_f32 v[32:33], v[32:33], v[34:35]
	s_nop 1
	v_exp_f32_e32 v2, v2
	v_cvt_pk_bf16_f32 v35, v32, v33
	v_lshl_add_u64 v[32:33], v[74:75], 0, v[92:93]
	v_mov_b32_e32 v37, v2
	v_pk_mul_f32 v[36:37], v[148:149], v[36:37]
	v_cvt_pk_bf16_f32 v34, v50, v51
	global_store_dwordx2 v[32:33], v[34:35], off
	v_cvt_pk_bf16_f32 v32, v48, v49
	v_cvt_pk_bf16_f32 v33, v36, v37
	v_lshl_add_u64 v[34:35], v[70:71], 0, v[92:93]
	v_lshlrev_b32_e32 v2, 1, v19
	global_store_dwordx2 v[34:35], v[32:33], off
	v_cvt_pk_bf16_f32 v32, v98, v44
	v_cvt_pk_bf16_f32 v33, v160, v46
	v_cvt_pk_bf16_f32 v34, v161, v52
	v_cvt_pk_bf16_f32 v35, v165, v48
	v_lshl_add_u64 v[42:43], v[40:41], 0, v[2:3]
	global_store_dwordx4 v[42:43], v[32:35], off
	v_lshl_add_u64 v[42:43], v[40:41], 0, v[72:73]
	s_nop 0
	v_cvt_pk_bf16_f32 v32, v102, v45
	v_cvt_pk_bf16_f32 v33, v162, v47
	v_cvt_pk_bf16_f32 v34, v159, v53
	v_cvt_pk_bf16_f32 v35, v166, v49
	global_store_dwordx4 v[42:43], v[32:35], off
	v_lshl_add_u64 v[42:43], v[40:41], 0, v[94:95]
	s_nop 0
	v_cvt_pk_bf16_f32 v32, v108, v28
	v_cvt_pk_bf16_f32 v33, v66, v30
	v_cvt_pk_bf16_f32 v34, v27, v38
	v_cvt_pk_bf16_f32 v35, v23, v36
	global_store_dwordx4 v[42:43], v[32:35], off
	v_cvt_pk_bf16_f32 v28, v144, v29
	v_cvt_pk_bf16_f32 v29, v67, v31
	v_cvt_pk_bf16_f32 v30, v25, v39
	v_cvt_pk_bf16_f32 v31, v58, v37
	v_lshl_add_u64 v[32:33], v[40:41], 0, v[96:97]
	global_store_dwordx4 v[32:33], v[28:31], off
	s_and_saveexec_b64 s[26:27], s[4:5]
	s_cbranch_execz .LBB0_174
	v_add_f32_e32 v4, v4, v152
	s_mov_b32 s28, 0xc2fc0000
	v_add_f32_e32 v4, v5, v4
	v_cmp_gt_f32_e32 vcc, s28, v99
	v_add_f32_e32 v5, v91, v4
	v_add_f32_e32 v4, v6, v100
	v_cndmask_b32_e32 v6, 0, v237, vcc
	v_add_f32_e32 v6, v99, v6
	v_exp_f32_e32 v6, v6
	v_add_f32_e32 v4, v7, v4
	v_sub_f32_e32 v5, v5, v99
	v_add_f32_e32 v23, v151, v4
	v_cndmask_b32_e32 v4, 0, v238, vcc
	v_cmp_gt_f32_e32 vcc, s28, v5
	v_ldexp_f32 v4, v6, v4
	v_add_f32_e32 v19, v82, v153
	v_cndmask_b32_e32 v6, 0, v237, vcc
	v_add_f32_e32 v5, v5, v6
	v_exp_f32_e32 v5, v5
	v_cndmask_b32_e32 v6, 0, v238, vcc
	v_cmp_gt_f32_e32 vcc, s28, v103
	v_add_f32_e32 v19, v83, v19
	v_ldexp_f32 v28, v5, v6
	v_cndmask_b32_e32 v6, 0, v237, vcc
	v_add_f32_e32 v6, v103, v6
	v_exp_f32_e32 v6, v6
	v_add_f32_e32 v19, v101, v19
	v_cndmask_b32_e32 v5, 0, v238, vcc
	v_add_f32_e32 v2, v80, v90
	v_ldexp_f32 v5, v6, v5
	v_sub_f32_e32 v6, v19, v103
	v_cmp_gt_f32_e32 vcc, s28, v6
	v_add_f32_e32 v2, v81, v2
	v_add_f32_e32 v2, v147, v2
	v_cndmask_b32_e32 v7, 0, v237, vcc
	v_add_f32_e32 v6, v6, v7
	v_exp_f32_e32 v6, v6
	v_cndmask_b32_e32 v7, 0, v238, vcc
	v_cmp_gt_f32_e32 vcc, s28, v109
	v_sub_f32_e32 v2, v2, v109
	v_ldexp_f32 v29, v6, v7
	v_cndmask_b32_e32 v7, 0, v237, vcc
	v_add_f32_e32 v7, v109, v7
	v_exp_f32_e32 v7, v7
	v_cndmask_b32_e32 v6, 0, v238, vcc
	v_cmp_gt_f32_e32 vcc, s28, v2
	v_ldexp_f32 v6, v7, v6
	s_nop 0
	v_cndmask_b32_e32 v7, 0, v237, vcc
	v_add_f32_e32 v2, v2, v7
	v_exp_f32_e32 v2, v2
	v_cndmask_b32_e32 v7, 0, v238, vcc
	v_cmp_gt_f32_e32 vcc, s28, v145
	v_ldexp_f32 v30, v2, v7
	s_nop 0
	v_cndmask_b32_e32 v7, 0, v237, vcc
	v_add_f32_e32 v7, v145, v7
	v_exp_f32_e32 v7, v7
	v_cndmask_b32_e32 v2, 0, v238, vcc
	v_ldexp_f32 v7, v7, v2
	v_sub_f32_e32 v2, v23, v145
	v_cmp_gt_f32_e32 vcc, s28, v2
	global_store_dwordx4 v21, v[4:7], s[24:25] offset:1024
	s_nop 1
	v_cndmask_b32_e32 v4, 0, v237, vcc
	v_add_f32_e32 v2, v2, v4
	v_exp_f32_e32 v2, v2
	v_cndmask_b32_e32 v4, 0, v238, vcc
	v_ldexp_f32 v31, v2, v4
	global_store_dwordx4 v21, v[28:31], s[24:25] offset:1536
	s_branch .LBB0_174
